# K loops: 2x2-blocked snake order over the 4x4 A/B fragment grid of each k half (fewer operand switches between consecutive MFMAs)
# baseline (speedup 1.0000x reference)
.Lsp_p1:
.LBB0_277:
	ds_read_b128 v[148:151], v145
	ds_read_b128 v[152:155], v145 offset:1024
	ds_read_b128 v[156:159], v145 offset:2048
	ds_read_b128 v[160:163], v145 offset:3072
	ds_read_b128 v[166:169], v146
	ds_read_b128 v[170:173], v146 offset:1024
	ds_read_b128 v[174:177], v146 offset:2048
	ds_read_b128 v[178:181], v146 offset:3072
	s_add_u32 s28, s26, 0xfff80080
	s_addc_u32 s29, s27, -1
	s_cmp_eq_u32 s50, 28
	s_cselect_b32 s31, s2, s29
	s_cselect_b32 s30, s13, s28
	s_cselect_b32 s29, s15, s33
	s_cselect_b32 s28, s23, s25
	v_lshl_add_u64 v[214:215], s[26:27], 0, v[138:139]
	s_add_i32 m0, s37, 0xc000
	ds_read_b128 v[182:185], v147
	ds_read_b128 v[186:189], v147 offset:1024
	ds_read_b128 v[190:193], v147 offset:2048
	ds_read_b128 v[194:197], v147 offset:3072
	ds_read_b128 v[198:201], v147 offset:4096
	ds_read_b128 v[202:205], v147 offset:5120
	ds_read_b128 v[206:209], v147 offset:6144
	ds_read_b128 v[210:213], v147 offset:7168
	global_load_lds_dwordx4 v[214:215], off
	v_lshl_add_u64 v[214:215], s[26:27], 0, v[140:141]
	s_add_i32 m0, s37, 0xe000
	s_nop 0
	global_load_lds_dwordx4 v[214:215], off
	s_waitcnt vmcnt(8)
	s_waitcnt lgkmcnt(0)
	s_barrier
	v_mfma_f32_16x16x32_bf16 v[126:129], v[148:151], v[182:185], v[126:129]
	v_mfma_f32_16x16x32_bf16 v[122:125], v[156:159], v[182:185], v[122:125]
	v_mfma_f32_16x16x32_bf16 v[106:109], v[156:159], v[190:193], v[106:109]
	v_mfma_f32_16x16x32_bf16 v[110:113], v[148:151], v[190:193], v[110:113]
	v_mfma_f32_16x16x32_bf16 v[94:97], v[148:151], v[198:201], v[94:97]
	v_mfma_f32_16x16x32_bf16 v[90:93], v[156:159], v[198:201], v[90:93]
	v_mfma_f32_16x16x32_bf16 v[74:77], v[156:159], v[206:209], v[74:77]
	v_mfma_f32_16x16x32_bf16 v[78:81], v[148:151], v[206:209], v[78:81]
	v_mfma_f32_16x16x32_bf16 v[70:73], v[166:169], v[206:209], v[70:73]
	v_mfma_f32_16x16x32_bf16 v[66:69], v[174:177], v[206:209], v[66:69]
	v_mfma_f32_16x16x32_bf16 v[82:85], v[174:177], v[198:201], v[82:85]
	v_mfma_f32_16x16x32_bf16 v[86:89], v[166:169], v[198:201], v[86:89]
	v_mfma_f32_16x16x32_bf16 v[102:105], v[166:169], v[190:193], v[102:105]
	v_mfma_f32_16x16x32_bf16 v[98:101], v[174:177], v[190:193], v[98:101]
	v_mfma_f32_16x16x32_bf16 v[114:117], v[174:177], v[182:185], v[114:117]
	v_mfma_f32_16x16x32_bf16 v[118:121], v[166:169], v[182:185], v[118:121]
	v_mfma_f32_16x16x32_bf16 v[126:129], v[152:155], v[186:189], v[126:129]
	v_mfma_f32_16x16x32_bf16 v[122:125], v[160:163], v[186:189], v[122:125]
	v_mfma_f32_16x16x32_bf16 v[106:109], v[160:163], v[194:197], v[106:109]
	v_mfma_f32_16x16x32_bf16 v[110:113], v[152:155], v[194:197], v[110:113]
	v_mfma_f32_16x16x32_bf16 v[94:97], v[152:155], v[202:205], v[94:97]
	v_mfma_f32_16x16x32_bf16 v[90:93], v[160:163], v[202:205], v[90:93]
	v_mfma_f32_16x16x32_bf16 v[74:77], v[160:163], v[210:213], v[74:77]
	v_mfma_f32_16x16x32_bf16 v[78:81], v[152:155], v[210:213], v[78:81]
	v_mfma_f32_16x16x32_bf16 v[70:73], v[170:173], v[210:213], v[70:73]
	v_mfma_f32_16x16x32_bf16 v[66:69], v[178:181], v[210:213], v[66:69]
	v_mfma_f32_16x16x32_bf16 v[82:85], v[178:181], v[202:205], v[82:85]
	v_mfma_f32_16x16x32_bf16 v[86:89], v[170:173], v[202:205], v[86:89]
	v_mfma_f32_16x16x32_bf16 v[102:105], v[170:173], v[194:197], v[102:105]
	v_mfma_f32_16x16x32_bf16 v[98:101], v[178:181], v[194:197], v[98:101]
	v_mfma_f32_16x16x32_bf16 v[114:117], v[178:181], v[186:189], v[114:117]
	v_mfma_f32_16x16x32_bf16 v[118:121], v[170:173], v[186:189], v[118:121]
	s_barrier
	s_add_i32 s51, s48, s36
	v_lshl_add_u64 v[214:215], s[28:29], 0, v[132:133]
	s_mov_b32 m0, s51
	ds_read_b128 v[182:185], v147 offset:16384
	ds_read_b128 v[186:189], v147 offset:17408
	ds_read_b128 v[190:193], v147 offset:18432
	ds_read_b128 v[194:197], v147 offset:19456
	ds_read_b128 v[198:201], v147 offset:20480
	ds_read_b128 v[202:205], v147 offset:21504
	ds_read_b128 v[206:209], v147 offset:22528
	ds_read_b128 v[210:213], v147 offset:23552
	global_load_lds_dwordx4 v[214:215], off
	s_add_i32 m0, s51, 0x2000
	s_add_u32 s52, s28, 0x80000
	v_lshl_add_u64 v[216:217], s[28:29], 0, v[136:137]
	s_addc_u32 s53, s29, 0
	s_add_i32 s51, s49, s36
	global_load_lds_dwordx4 v[216:217], off
	v_lshl_add_u64 v[218:219], s[52:53], 0, v[132:133]
	s_mov_b32 m0, s51
	v_lshl_add_u64 v[220:221], s[30:31], 0, v[134:135]
	global_load_lds_dwordx4 v[218:219], off
	v_lshl_add_u64 v[218:219], s[52:53], 0, v[136:137]
	s_add_i32 m0, s51, 0x2000
	s_nop 0
	global_load_lds_dwordx4 v[218:219], off
	v_lshl_add_u64 v[218:219], s[30:31], 0, v[130:131]
	s_mov_b32 m0, s37
	s_nop 0
	global_load_lds_dwordx4 v[218:219], off
	s_mov_b32 m0, s38
	s_nop 0
	global_load_lds_dwordx4 v[220:221], off
	s_waitcnt vmcnt(8)
	s_waitcnt lgkmcnt(0)
	s_barrier
	v_mfma_f32_16x16x32_bf16 v[62:65], v[148:151], v[182:185], v[62:65]
	v_mfma_f32_16x16x32_bf16 v[58:61], v[156:159], v[182:185], v[58:61]
	v_mfma_f32_16x16x32_bf16 v[42:45], v[156:159], v[190:193], v[42:45]
	v_mfma_f32_16x16x32_bf16 v[46:49], v[148:151], v[190:193], v[46:49]
	v_mfma_f32_16x16x32_bf16 v[30:33], v[148:151], v[198:201], v[30:33]
	v_mfma_f32_16x16x32_bf16 v[26:29], v[156:159], v[198:201], v[26:29]
	v_mfma_f32_16x16x32_bf16 v[10:13], v[156:159], v[206:209], v[10:13]
	v_mfma_f32_16x16x32_bf16 v[14:17], v[148:151], v[206:209], v[14:17]
	v_mfma_f32_16x16x32_bf16 v[6:9], v[166:169], v[206:209], v[6:9]
	v_mfma_f32_16x16x32_bf16 v[2:5], v[174:177], v[206:209], v[2:5]
	v_mfma_f32_16x16x32_bf16 v[18:21], v[174:177], v[198:201], v[18:21]
	v_mfma_f32_16x16x32_bf16 v[22:25], v[166:169], v[198:201], v[22:25]
	v_mfma_f32_16x16x32_bf16 v[38:41], v[166:169], v[190:193], v[38:41]
	v_mfma_f32_16x16x32_bf16 v[34:37], v[174:177], v[190:193], v[34:37]
	v_mfma_f32_16x16x32_bf16 v[50:53], v[174:177], v[182:185], v[50:53]
	v_mfma_f32_16x16x32_bf16 v[54:57], v[166:169], v[182:185], v[54:57]
	v_mfma_f32_16x16x32_bf16 v[62:65], v[152:155], v[186:189], v[62:65]
	v_mfma_f32_16x16x32_bf16 v[58:61], v[160:163], v[186:189], v[58:61]
	v_mfma_f32_16x16x32_bf16 v[42:45], v[160:163], v[194:197], v[42:45]
	v_mfma_f32_16x16x32_bf16 v[46:49], v[152:155], v[194:197], v[46:49]
	v_mfma_f32_16x16x32_bf16 v[30:33], v[152:155], v[202:205], v[30:33]
	v_mfma_f32_16x16x32_bf16 v[26:29], v[160:163], v[202:205], v[26:29]
	v_mfma_f32_16x16x32_bf16 v[10:13], v[160:163], v[210:213], v[10:13]
	v_mfma_f32_16x16x32_bf16 v[14:17], v[152:155], v[210:213], v[14:17]
	v_mfma_f32_16x16x32_bf16 v[6:9], v[170:173], v[210:213], v[6:9]
	v_mfma_f32_16x16x32_bf16 v[2:5], v[178:181], v[210:213], v[2:5]
	v_mfma_f32_16x16x32_bf16 v[18:21], v[178:181], v[202:205], v[18:21]
	v_mfma_f32_16x16x32_bf16 v[22:25], v[170:173], v[202:205], v[22:25]
	v_mfma_f32_16x16x32_bf16 v[38:41], v[170:173], v[194:197], v[38:41]
	v_mfma_f32_16x16x32_bf16 v[34:37], v[178:181], v[194:197], v[34:37]
	v_mfma_f32_16x16x32_bf16 v[50:53], v[178:181], v[186:189], v[50:53]
	v_mfma_f32_16x16x32_bf16 v[54:57], v[170:173], v[186:189], v[54:57]
	s_barrier
	s_add_i32 s51, 0, 0x18000
	s_add_i32 s52, 0, 0x1c000
	v_add_u32_e32 v160, s51, v144
	v_add_u32_e32 v164, s52, v144
	ds_read_b128 v[148:151], v160
	ds_read_b128 v[152:155], v160 offset:1024
	ds_read_b128 v[156:159], v160 offset:2048
	ds_read_b128 v[160:163], v160 offset:3072
	ds_read_b128 v[166:169], v164
	ds_read_b128 v[170:173], v164 offset:1024
	ds_read_b128 v[174:177], v164 offset:2048
	ds_read_b128 v[178:181], v164 offset:3072
	s_add_u32 s30, s30, 0x80000
	s_addc_u32 s31, s31, 0
	s_mov_b32 m0, s39
	v_lshl_add_u64 v[222:223], s[30:31], 0, v[130:131]
	ds_read_b128 v[182:185], v147 offset:32768
	ds_read_b128 v[186:189], v147 offset:33792
	ds_read_b128 v[190:193], v147 offset:34816
	ds_read_b128 v[194:197], v147 offset:35840
	ds_read_b128 v[198:201], v147 offset:36864
	ds_read_b128 v[202:205], v147 offset:37888
	ds_read_b128 v[206:209], v147 offset:38912
	ds_read_b128 v[210:213], v147 offset:39936
	global_load_lds_dwordx4 v[222:223], off
	v_lshl_add_u64 v[222:223], s[30:31], 0, v[134:135]
	s_mov_b32 m0, s40
	s_nop 0
	global_load_lds_dwordx4 v[222:223], off
	s_waitcnt vmcnt(8)
	s_waitcnt lgkmcnt(0)
	s_barrier
	v_mfma_f32_16x16x32_bf16 v[126:129], v[148:151], v[182:185], v[126:129]
	v_mfma_f32_16x16x32_bf16 v[122:125], v[156:159], v[182:185], v[122:125]
	v_mfma_f32_16x16x32_bf16 v[106:109], v[156:159], v[190:193], v[106:109]
	v_mfma_f32_16x16x32_bf16 v[110:113], v[148:151], v[190:193], v[110:113]
	v_mfma_f32_16x16x32_bf16 v[94:97], v[148:151], v[198:201], v[94:97]
	v_mfma_f32_16x16x32_bf16 v[90:93], v[156:159], v[198:201], v[90:93]
	v_mfma_f32_16x16x32_bf16 v[74:77], v[156:159], v[206:209], v[74:77]
	v_mfma_f32_16x16x32_bf16 v[78:81], v[148:151], v[206:209], v[78:81]
	v_mfma_f32_16x16x32_bf16 v[70:73], v[166:169], v[206:209], v[70:73]
	v_mfma_f32_16x16x32_bf16 v[66:69], v[174:177], v[206:209], v[66:69]
	v_mfma_f32_16x16x32_bf16 v[82:85], v[174:177], v[198:201], v[82:85]
	v_mfma_f32_16x16x32_bf16 v[86:89], v[166:169], v[198:201], v[86:89]
	v_mfma_f32_16x16x32_bf16 v[102:105], v[166:169], v[190:193], v[102:105]
	v_mfma_f32_16x16x32_bf16 v[98:101], v[174:177], v[190:193], v[98:101]
	v_mfma_f32_16x16x32_bf16 v[114:117], v[174:177], v[182:185], v[114:117]
	v_mfma_f32_16x16x32_bf16 v[118:121], v[166:169], v[182:185], v[118:121]
	v_mfma_f32_16x16x32_bf16 v[126:129], v[152:155], v[186:189], v[126:129]
	v_mfma_f32_16x16x32_bf16 v[122:125], v[160:163], v[186:189], v[122:125]
	v_mfma_f32_16x16x32_bf16 v[106:109], v[160:163], v[194:197], v[106:109]
	v_mfma_f32_16x16x32_bf16 v[110:113], v[152:155], v[194:197], v[110:113]
	v_mfma_f32_16x16x32_bf16 v[94:97], v[152:155], v[202:205], v[94:97]
	v_mfma_f32_16x16x32_bf16 v[90:93], v[160:163], v[202:205], v[90:93]
	v_mfma_f32_16x16x32_bf16 v[74:77], v[160:163], v[210:213], v[74:77]
	v_mfma_f32_16x16x32_bf16 v[78:81], v[152:155], v[210:213], v[78:81]
	v_mfma_f32_16x16x32_bf16 v[70:73], v[170:173], v[210:213], v[70:73]
	v_mfma_f32_16x16x32_bf16 v[66:69], v[178:181], v[210:213], v[66:69]
	v_mfma_f32_16x16x32_bf16 v[82:85], v[178:181], v[202:205], v[82:85]
	v_mfma_f32_16x16x32_bf16 v[86:89], v[170:173], v[202:205], v[86:89]
	v_mfma_f32_16x16x32_bf16 v[102:105], v[170:173], v[194:197], v[102:105]
	v_mfma_f32_16x16x32_bf16 v[98:101], v[178:181], v[194:197], v[98:101]
	v_mfma_f32_16x16x32_bf16 v[114:117], v[178:181], v[186:189], v[114:117]
	v_mfma_f32_16x16x32_bf16 v[118:121], v[170:173], v[186:189], v[118:121]
	s_barrier
	s_add_i32 s30, s51, s36
	v_lshl_add_u64 v[214:215], v[214:215], 0, s[8:9]
	s_mov_b32 m0, s30
	ds_read_b128 v[182:185], v147 offset:49152
	ds_read_b128 v[186:189], v147 offset:50176
	ds_read_b128 v[190:193], v147 offset:51200
	ds_read_b128 v[194:197], v147 offset:52224
	ds_read_b128 v[198:201], v147 offset:53248
	ds_read_b128 v[202:205], v147 offset:54272
	ds_read_b128 v[206:209], v147 offset:55296
	ds_read_b128 v[210:213], v147 offset:56320
	global_load_lds_dwordx4 v[214:215], off
	s_add_i32 m0, s30, 0x2000
	s_add_u32 s28, s28, 0x80080
	v_lshl_add_u64 v[214:215], v[216:217], 0, s[8:9]
	s_addc_u32 s29, s29, 0
	s_add_i32 s30, s52, s36
	global_load_lds_dwordx4 v[214:215], off
	v_lshl_add_u64 v[214:215], s[28:29], 0, v[132:133]
	s_mov_b32 m0, s30
	s_nop 0
	global_load_lds_dwordx4 v[214:215], off
	v_lshl_add_u64 v[214:215], s[28:29], 0, v[136:137]
	s_add_i32 m0, s30, 0x2000
	s_nop 0
	global_load_lds_dwordx4 v[214:215], off
	v_lshl_add_u64 v[214:215], v[218:219], 0, s[8:9]
	s_mov_b32 m0, s44
	s_nop 0
	global_load_lds_dwordx4 v[214:215], off
	v_lshl_add_u64 v[214:215], v[220:221], 0, s[8:9]
	s_mov_b32 m0, s45
	s_nop 0
	global_load_lds_dwordx4 v[214:215], off
	s_waitcnt vmcnt(8)
	s_waitcnt lgkmcnt(0)
	s_barrier
	v_mfma_f32_16x16x32_bf16 v[62:65], v[148:151], v[182:185], v[62:65]
	v_mfma_f32_16x16x32_bf16 v[58:61], v[156:159], v[182:185], v[58:61]
	v_mfma_f32_16x16x32_bf16 v[42:45], v[156:159], v[190:193], v[42:45]
	v_mfma_f32_16x16x32_bf16 v[46:49], v[148:151], v[190:193], v[46:49]
	v_mfma_f32_16x16x32_bf16 v[30:33], v[148:151], v[198:201], v[30:33]
	v_mfma_f32_16x16x32_bf16 v[26:29], v[156:159], v[198:201], v[26:29]
	v_mfma_f32_16x16x32_bf16 v[10:13], v[156:159], v[206:209], v[10:13]
	v_mfma_f32_16x16x32_bf16 v[14:17], v[148:151], v[206:209], v[14:17]
	v_mfma_f32_16x16x32_bf16 v[6:9], v[166:169], v[206:209], v[6:9]
	v_mfma_f32_16x16x32_bf16 v[2:5], v[174:177], v[206:209], v[2:5]
	v_mfma_f32_16x16x32_bf16 v[18:21], v[174:177], v[198:201], v[18:21]
	v_mfma_f32_16x16x32_bf16 v[22:25], v[166:169], v[198:201], v[22:25]
	v_mfma_f32_16x16x32_bf16 v[38:41], v[166:169], v[190:193], v[38:41]
	v_mfma_f32_16x16x32_bf16 v[34:37], v[174:177], v[190:193], v[34:37]
	v_mfma_f32_16x16x32_bf16 v[50:53], v[174:177], v[182:185], v[50:53]
	v_mfma_f32_16x16x32_bf16 v[54:57], v[166:169], v[182:185], v[54:57]
	v_mfma_f32_16x16x32_bf16 v[62:65], v[152:155], v[186:189], v[62:65]
	v_mfma_f32_16x16x32_bf16 v[58:61], v[160:163], v[186:189], v[58:61]
	v_mfma_f32_16x16x32_bf16 v[42:45], v[160:163], v[194:197], v[42:45]
	v_mfma_f32_16x16x32_bf16 v[46:49], v[152:155], v[194:197], v[46:49]
	v_mfma_f32_16x16x32_bf16 v[30:33], v[152:155], v[202:205], v[30:33]
	v_mfma_f32_16x16x32_bf16 v[26:29], v[160:163], v[202:205], v[26:29]
	v_mfma_f32_16x16x32_bf16 v[10:13], v[160:163], v[210:213], v[10:13]
	v_mfma_f32_16x16x32_bf16 v[14:17], v[152:155], v[210:213], v[14:17]
	v_mfma_f32_16x16x32_bf16 v[6:9], v[170:173], v[210:213], v[6:9]
	v_mfma_f32_16x16x32_bf16 v[2:5], v[178:181], v[210:213], v[2:5]
	v_mfma_f32_16x16x32_bf16 v[18:21], v[178:181], v[202:205], v[18:21]
	v_mfma_f32_16x16x32_bf16 v[22:25], v[170:173], v[202:205], v[22:25]
	v_mfma_f32_16x16x32_bf16 v[38:41], v[170:173], v[194:197], v[38:41]
	v_mfma_f32_16x16x32_bf16 v[34:37], v[178:181], v[194:197], v[34:37]
	v_mfma_f32_16x16x32_bf16 v[50:53], v[178:181], v[186:189], v[50:53]
	v_mfma_f32_16x16x32_bf16 v[54:57], v[170:173], v[186:189], v[54:57]
	s_barrier
	s_add_i32 s50, s50, 2
	s_add_u32 s26, s26, 0x100
	s_addc_u32 s27, s27, 0
	s_add_u32 s25, s25, 0x100
	s_addc_u32 s33, s33, 0
	s_cmp_gt_u32 s50, 29
	s_cbranch_scc0 .LBB0_277
	s_setprio 0
	s_and_b64 vcc, exec, s[10:11]
	s_cbranch_vccz .LBB0_280
	s_barrier

.Lsp_p4:
.LBB0_704:
	ds_read_b128 v[144:147], v152
	ds_read_b128 v[156:159], v152 offset:1024
	ds_read_b128 v[160:163], v152 offset:2048
	ds_read_b128 v[166:169], v152 offset:3072
	ds_read_b128 v[170:173], v153
	ds_read_b128 v[174:177], v153 offset:1024
	ds_read_b128 v[178:181], v153 offset:2048
	ds_read_b128 v[182:185], v153 offset:3072
	s_add_u32 s24, s22, 0xfff80080
	s_addc_u32 s25, s23, -1
	s_cmp_eq_u32 s45, 28
	s_cselect_b32 s27, s17, s25
	s_cselect_b32 s26, s16, s24
	s_cselect_b32 s25, s21, s15
	s_cselect_b32 s24, s20, s5
	s_mov_b32 m0, s42
	v_lshl_add_u64 v[218:219], s[22:23], 0, v[140:141]
	ds_read_b128 v[186:189], v154
	ds_read_b128 v[190:193], v154 offset:1024
	ds_read_b128 v[194:197], v154 offset:2048
	ds_read_b128 v[198:201], v154 offset:3072
	ds_read_b128 v[202:205], v154 offset:4096
	ds_read_b128 v[206:209], v154 offset:5120
	ds_read_b128 v[210:213], v154 offset:6144
	ds_read_b128 v[214:217], v154 offset:7168
	global_load_lds_dwordx4 v[218:219], off
	v_lshl_add_u64 v[218:219], s[22:23], 0, v[142:143]
	s_add_i32 m0, s30, 0xe000
	s_nop 0
	global_load_lds_dwordx4 v[218:219], off
	s_waitcnt vmcnt(8)
	s_waitcnt lgkmcnt(0)
	s_barrier
	v_mfma_f32_16x16x32_bf16 v[126:129], v[144:147], v[186:189], v[126:129]
	v_mfma_f32_16x16x32_bf16 v[122:125], v[160:163], v[186:189], v[122:125]
	v_mfma_f32_16x16x32_bf16 v[106:109], v[160:163], v[194:197], v[106:109]
	v_mfma_f32_16x16x32_bf16 v[110:113], v[144:147], v[194:197], v[110:113]
	v_mfma_f32_16x16x32_bf16 v[94:97], v[144:147], v[202:205], v[94:97]
	v_mfma_f32_16x16x32_bf16 v[90:93], v[160:163], v[202:205], v[90:93]
	v_mfma_f32_16x16x32_bf16 v[74:77], v[160:163], v[210:213], v[74:77]
	v_mfma_f32_16x16x32_bf16 v[78:81], v[144:147], v[210:213], v[78:81]
	v_mfma_f32_16x16x32_bf16 v[70:73], v[170:173], v[210:213], v[70:73]
	v_mfma_f32_16x16x32_bf16 v[66:69], v[178:181], v[210:213], v[66:69]
	v_mfma_f32_16x16x32_bf16 v[82:85], v[178:181], v[202:205], v[82:85]
	v_mfma_f32_16x16x32_bf16 v[86:89], v[170:173], v[202:205], v[86:89]
	v_mfma_f32_16x16x32_bf16 v[102:105], v[170:173], v[194:197], v[102:105]
	v_mfma_f32_16x16x32_bf16 v[98:101], v[178:181], v[194:197], v[98:101]
	v_mfma_f32_16x16x32_bf16 v[114:117], v[178:181], v[186:189], v[114:117]
	v_mfma_f32_16x16x32_bf16 v[118:121], v[170:173], v[186:189], v[118:121]
	v_mfma_f32_16x16x32_bf16 v[126:129], v[156:159], v[190:193], v[126:129]
	v_mfma_f32_16x16x32_bf16 v[122:125], v[166:169], v[190:193], v[122:125]
	v_mfma_f32_16x16x32_bf16 v[106:109], v[166:169], v[198:201], v[106:109]
	v_mfma_f32_16x16x32_bf16 v[110:113], v[156:159], v[198:201], v[110:113]
	v_mfma_f32_16x16x32_bf16 v[94:97], v[156:159], v[206:209], v[94:97]
	v_mfma_f32_16x16x32_bf16 v[90:93], v[166:169], v[206:209], v[90:93]
	v_mfma_f32_16x16x32_bf16 v[74:77], v[166:169], v[214:217], v[74:77]
	v_mfma_f32_16x16x32_bf16 v[78:81], v[156:159], v[214:217], v[78:81]
	v_mfma_f32_16x16x32_bf16 v[70:73], v[174:177], v[214:217], v[70:73]
	v_mfma_f32_16x16x32_bf16 v[66:69], v[182:185], v[214:217], v[66:69]
	v_mfma_f32_16x16x32_bf16 v[82:85], v[182:185], v[206:209], v[82:85]
	v_mfma_f32_16x16x32_bf16 v[86:89], v[174:177], v[206:209], v[86:89]
	v_mfma_f32_16x16x32_bf16 v[102:105], v[174:177], v[198:201], v[102:105]
	v_mfma_f32_16x16x32_bf16 v[98:101], v[182:185], v[198:201], v[98:101]
	v_mfma_f32_16x16x32_bf16 v[114:117], v[182:185], v[190:193], v[114:117]
	v_mfma_f32_16x16x32_bf16 v[118:121], v[174:177], v[190:193], v[118:121]
	s_barrier
	s_add_i32 s46, s40, s29
	v_lshl_add_u64 v[218:219], s[24:25], 0, v[134:135]
	s_mov_b32 m0, s46
	ds_read_b128 v[186:189], v154 offset:16384
	ds_read_b128 v[190:193], v154 offset:17408
	ds_read_b128 v[194:197], v154 offset:18432
	ds_read_b128 v[198:201], v154 offset:19456
	ds_read_b128 v[202:205], v154 offset:20480
	ds_read_b128 v[206:209], v154 offset:21504
	ds_read_b128 v[210:213], v154 offset:22528
	ds_read_b128 v[214:217], v154 offset:23552
	global_load_lds_dwordx4 v[218:219], off
	s_add_i32 m0, s46, 0x2000
	s_add_u32 s46, s24, 0x80000
	v_lshl_add_u64 v[220:221], s[24:25], 0, v[138:139]
	s_addc_u32 s47, s25, 0
	s_add_i32 s48, s41, s29
	global_load_lds_dwordx4 v[220:221], off
	v_lshl_add_u64 v[222:223], s[46:47], 0, v[134:135]
	s_mov_b32 m0, s48
	v_lshl_add_u64 v[224:225], s[26:27], 0, v[136:137]
	global_load_lds_dwordx4 v[222:223], off
	v_lshl_add_u64 v[222:223], s[46:47], 0, v[138:139]
	s_add_i32 m0, s48, 0x2000
	s_nop 0
	global_load_lds_dwordx4 v[222:223], off
	v_lshl_add_u64 v[222:223], s[26:27], 0, v[132:133]
	s_mov_b32 m0, s30
	s_nop 0
	global_load_lds_dwordx4 v[222:223], off
	s_mov_b32 m0, s31
	s_nop 0
	global_load_lds_dwordx4 v[224:225], off
	s_waitcnt vmcnt(8)
	s_waitcnt lgkmcnt(0)
	s_barrier
	v_mfma_f32_16x16x32_bf16 v[62:65], v[144:147], v[186:189], v[62:65]
	v_mfma_f32_16x16x32_bf16 v[58:61], v[160:163], v[186:189], v[58:61]
	v_mfma_f32_16x16x32_bf16 v[42:45], v[160:163], v[194:197], v[42:45]
	v_mfma_f32_16x16x32_bf16 v[46:49], v[144:147], v[194:197], v[46:49]
	v_mfma_f32_16x16x32_bf16 v[30:33], v[144:147], v[202:205], v[30:33]
	v_mfma_f32_16x16x32_bf16 v[26:29], v[160:163], v[202:205], v[26:29]
	v_mfma_f32_16x16x32_bf16 v[10:13], v[160:163], v[210:213], v[10:13]
	v_mfma_f32_16x16x32_bf16 v[14:17], v[144:147], v[210:213], v[14:17]
	v_mfma_f32_16x16x32_bf16 v[6:9], v[170:173], v[210:213], v[6:9]
	v_mfma_f32_16x16x32_bf16 v[2:5], v[178:181], v[210:213], v[2:5]
	v_mfma_f32_16x16x32_bf16 v[18:21], v[178:181], v[202:205], v[18:21]
	v_mfma_f32_16x16x32_bf16 v[22:25], v[170:173], v[202:205], v[22:25]
	v_mfma_f32_16x16x32_bf16 v[38:41], v[170:173], v[194:197], v[38:41]
	v_mfma_f32_16x16x32_bf16 v[34:37], v[178:181], v[194:197], v[34:37]
	v_mfma_f32_16x16x32_bf16 v[50:53], v[178:181], v[186:189], v[50:53]
	v_mfma_f32_16x16x32_bf16 v[54:57], v[170:173], v[186:189], v[54:57]
	v_mfma_f32_16x16x32_bf16 v[62:65], v[156:159], v[190:193], v[62:65]
	v_mfma_f32_16x16x32_bf16 v[58:61], v[166:169], v[190:193], v[58:61]
	v_mfma_f32_16x16x32_bf16 v[42:45], v[166:169], v[198:201], v[42:45]
	v_mfma_f32_16x16x32_bf16 v[46:49], v[156:159], v[198:201], v[46:49]
	v_mfma_f32_16x16x32_bf16 v[30:33], v[156:159], v[206:209], v[30:33]
	v_mfma_f32_16x16x32_bf16 v[26:29], v[166:169], v[206:209], v[26:29]
	v_mfma_f32_16x16x32_bf16 v[10:13], v[166:169], v[214:217], v[10:13]
	v_mfma_f32_16x16x32_bf16 v[14:17], v[156:159], v[214:217], v[14:17]
	v_mfma_f32_16x16x32_bf16 v[6:9], v[174:177], v[214:217], v[6:9]
	v_mfma_f32_16x16x32_bf16 v[2:5], v[182:185], v[214:217], v[2:5]
	v_mfma_f32_16x16x32_bf16 v[18:21], v[182:185], v[206:209], v[18:21]
	v_mfma_f32_16x16x32_bf16 v[22:25], v[174:177], v[206:209], v[22:25]
	v_mfma_f32_16x16x32_bf16 v[38:41], v[174:177], v[198:201], v[38:41]
	v_mfma_f32_16x16x32_bf16 v[34:37], v[182:185], v[198:201], v[34:37]
	v_mfma_f32_16x16x32_bf16 v[50:53], v[182:185], v[190:193], v[50:53]
	v_mfma_f32_16x16x32_bf16 v[54:57], v[174:177], v[190:193], v[54:57]
	s_barrier
	s_add_i32 s46, 0, 0x18000
	v_add_u32_e32 v155, s46, v1
	s_add_i32 s47, 0, 0x1c000
	ds_read_b128 v[144:147], v155
	ds_read_b128 v[156:159], v155 offset:1024
	ds_read_b128 v[160:163], v155 offset:2048
	ds_read_b128 v[166:169], v155 offset:3072
	v_add_u32_e32 v155, s47, v1
	ds_read_b128 v[170:173], v155
	ds_read_b128 v[174:177], v155 offset:1024
	ds_read_b128 v[178:181], v155 offset:2048
	ds_read_b128 v[182:185], v155 offset:3072
	s_add_u32 s26, s26, 0x80000
	s_addc_u32 s27, s27, 0
	s_mov_b32 m0, s33
	v_lshl_add_u64 v[226:227], s[26:27], 0, v[132:133]
	ds_read_b128 v[186:189], v154 offset:32768
	ds_read_b128 v[190:193], v154 offset:33792
	ds_read_b128 v[194:197], v154 offset:34816
	ds_read_b128 v[198:201], v154 offset:35840
	ds_read_b128 v[202:205], v154 offset:36864
	ds_read_b128 v[206:209], v154 offset:37888
	ds_read_b128 v[210:213], v154 offset:38912
	ds_read_b128 v[214:217], v154 offset:39936
	global_load_lds_dwordx4 v[226:227], off
	v_lshl_add_u64 v[226:227], s[26:27], 0, v[136:137]
	s_mov_b32 m0, s34
	s_nop 0
	global_load_lds_dwordx4 v[226:227], off
	s_waitcnt vmcnt(8)
	s_waitcnt lgkmcnt(0)
	s_barrier
	v_mfma_f32_16x16x32_bf16 v[126:129], v[144:147], v[186:189], v[126:129]
	v_mfma_f32_16x16x32_bf16 v[122:125], v[160:163], v[186:189], v[122:125]
	v_mfma_f32_16x16x32_bf16 v[106:109], v[160:163], v[194:197], v[106:109]
	v_mfma_f32_16x16x32_bf16 v[110:113], v[144:147], v[194:197], v[110:113]
	v_mfma_f32_16x16x32_bf16 v[94:97], v[144:147], v[202:205], v[94:97]
	v_mfma_f32_16x16x32_bf16 v[90:93], v[160:163], v[202:205], v[90:93]
	v_mfma_f32_16x16x32_bf16 v[74:77], v[160:163], v[210:213], v[74:77]
	v_mfma_f32_16x16x32_bf16 v[78:81], v[144:147], v[210:213], v[78:81]
	v_mfma_f32_16x16x32_bf16 v[70:73], v[170:173], v[210:213], v[70:73]
	v_mfma_f32_16x16x32_bf16 v[66:69], v[178:181], v[210:213], v[66:69]
	v_mfma_f32_16x16x32_bf16 v[82:85], v[178:181], v[202:205], v[82:85]
	v_mfma_f32_16x16x32_bf16 v[86:89], v[170:173], v[202:205], v[86:89]
	v_mfma_f32_16x16x32_bf16 v[102:105], v[170:173], v[194:197], v[102:105]
	v_mfma_f32_16x16x32_bf16 v[98:101], v[178:181], v[194:197], v[98:101]
	v_mfma_f32_16x16x32_bf16 v[114:117], v[178:181], v[186:189], v[114:117]
	v_mfma_f32_16x16x32_bf16 v[118:121], v[170:173], v[186:189], v[118:121]
	v_mfma_f32_16x16x32_bf16 v[126:129], v[156:159], v[190:193], v[126:129]
	v_mfma_f32_16x16x32_bf16 v[122:125], v[166:169], v[190:193], v[122:125]
	v_mfma_f32_16x16x32_bf16 v[106:109], v[166:169], v[198:201], v[106:109]
	v_mfma_f32_16x16x32_bf16 v[110:113], v[156:159], v[198:201], v[110:113]
	v_mfma_f32_16x16x32_bf16 v[94:97], v[156:159], v[206:209], v[94:97]
	v_mfma_f32_16x16x32_bf16 v[90:93], v[166:169], v[206:209], v[90:93]
	v_mfma_f32_16x16x32_bf16 v[74:77], v[166:169], v[214:217], v[74:77]
	v_mfma_f32_16x16x32_bf16 v[78:81], v[156:159], v[214:217], v[78:81]
	v_mfma_f32_16x16x32_bf16 v[70:73], v[174:177], v[214:217], v[70:73]
	v_mfma_f32_16x16x32_bf16 v[66:69], v[182:185], v[214:217], v[66:69]
	v_mfma_f32_16x16x32_bf16 v[82:85], v[182:185], v[206:209], v[82:85]
	v_mfma_f32_16x16x32_bf16 v[86:89], v[174:177], v[206:209], v[86:89]
	v_mfma_f32_16x16x32_bf16 v[102:105], v[174:177], v[198:201], v[102:105]
	v_mfma_f32_16x16x32_bf16 v[98:101], v[182:185], v[198:201], v[98:101]
	v_mfma_f32_16x16x32_bf16 v[114:117], v[182:185], v[190:193], v[114:117]
	v_mfma_f32_16x16x32_bf16 v[118:121], v[174:177], v[190:193], v[118:121]
	s_barrier
	s_add_i32 s26, s46, s29
	v_lshl_add_u64 v[218:219], v[218:219], 0, s[10:11]
	s_mov_b32 m0, s26
	ds_read_b128 v[186:189], v154 offset:49152
	ds_read_b128 v[190:193], v154 offset:50176
	ds_read_b128 v[194:197], v154 offset:51200
	ds_read_b128 v[198:201], v154 offset:52224
	ds_read_b128 v[202:205], v154 offset:53248
	ds_read_b128 v[206:209], v154 offset:54272
	ds_read_b128 v[210:213], v154 offset:55296
	ds_read_b128 v[214:217], v154 offset:56320
	global_load_lds_dwordx4 v[218:219], off
	s_add_i32 m0, s26, 0x2000
	s_add_u32 s24, s24, 0x80080
	v_lshl_add_u64 v[218:219], v[220:221], 0, s[10:11]
	s_addc_u32 s25, s25, 0
	s_add_i32 s26, s47, s29
	global_load_lds_dwordx4 v[218:219], off
	v_lshl_add_u64 v[218:219], s[24:25], 0, v[134:135]
	s_mov_b32 m0, s26
	s_nop 0
	global_load_lds_dwordx4 v[218:219], off
	v_lshl_add_u64 v[218:219], s[24:25], 0, v[138:139]
	s_add_i32 m0, s26, 0x2000
	s_nop 0
	global_load_lds_dwordx4 v[218:219], off
	v_lshl_add_u64 v[218:219], v[222:223], 0, s[10:11]
	s_mov_b32 m0, s38
	s_nop 0
	global_load_lds_dwordx4 v[218:219], off
	v_lshl_add_u64 v[218:219], v[224:225], 0, s[10:11]
	s_mov_b32 m0, s39
	s_nop 0
	global_load_lds_dwordx4 v[218:219], off
	s_waitcnt vmcnt(8)
	s_waitcnt lgkmcnt(0)
	s_barrier
	v_mfma_f32_16x16x32_bf16 v[62:65], v[144:147], v[186:189], v[62:65]
	v_mfma_f32_16x16x32_bf16 v[58:61], v[160:163], v[186:189], v[58:61]
	v_mfma_f32_16x16x32_bf16 v[42:45], v[160:163], v[194:197], v[42:45]
	v_mfma_f32_16x16x32_bf16 v[46:49], v[144:147], v[194:197], v[46:49]
	v_mfma_f32_16x16x32_bf16 v[30:33], v[144:147], v[202:205], v[30:33]
	v_mfma_f32_16x16x32_bf16 v[26:29], v[160:163], v[202:205], v[26:29]
	v_mfma_f32_16x16x32_bf16 v[10:13], v[160:163], v[210:213], v[10:13]
	v_mfma_f32_16x16x32_bf16 v[14:17], v[144:147], v[210:213], v[14:17]
	v_mfma_f32_16x16x32_bf16 v[6:9], v[170:173], v[210:213], v[6:9]
	v_mfma_f32_16x16x32_bf16 v[2:5], v[178:181], v[210:213], v[2:5]
	v_mfma_f32_16x16x32_bf16 v[18:21], v[178:181], v[202:205], v[18:21]
	v_mfma_f32_16x16x32_bf16 v[22:25], v[170:173], v[202:205], v[22:25]
	v_mfma_f32_16x16x32_bf16 v[38:41], v[170:173], v[194:197], v[38:41]
	v_mfma_f32_16x16x32_bf16 v[34:37], v[178:181], v[194:197], v[34:37]
	v_mfma_f32_16x16x32_bf16 v[50:53], v[178:181], v[186:189], v[50:53]
	v_mfma_f32_16x16x32_bf16 v[54:57], v[170:173], v[186:189], v[54:57]
	v_mfma_f32_16x16x32_bf16 v[62:65], v[156:159], v[190:193], v[62:65]
	v_mfma_f32_16x16x32_bf16 v[58:61], v[166:169], v[190:193], v[58:61]
	v_mfma_f32_16x16x32_bf16 v[42:45], v[166:169], v[198:201], v[42:45]
	v_mfma_f32_16x16x32_bf16 v[46:49], v[156:159], v[198:201], v[46:49]
	v_mfma_f32_16x16x32_bf16 v[30:33], v[156:159], v[206:209], v[30:33]
	v_mfma_f32_16x16x32_bf16 v[26:29], v[166:169], v[206:209], v[26:29]
	v_mfma_f32_16x16x32_bf16 v[10:13], v[166:169], v[214:217], v[10:13]
	v_mfma_f32_16x16x32_bf16 v[14:17], v[156:159], v[214:217], v[14:17]
	v_mfma_f32_16x16x32_bf16 v[6:9], v[174:177], v[214:217], v[6:9]
	v_mfma_f32_16x16x32_bf16 v[2:5], v[182:185], v[214:217], v[2:5]
	v_mfma_f32_16x16x32_bf16 v[18:21], v[182:185], v[206:209], v[18:21]
	v_mfma_f32_16x16x32_bf16 v[22:25], v[174:177], v[206:209], v[22:25]
	v_mfma_f32_16x16x32_bf16 v[38:41], v[174:177], v[198:201], v[38:41]
	v_mfma_f32_16x16x32_bf16 v[34:37], v[182:185], v[198:201], v[34:37]
	v_mfma_f32_16x16x32_bf16 v[50:53], v[182:185], v[190:193], v[50:53]
	v_mfma_f32_16x16x32_bf16 v[54:57], v[174:177], v[190:193], v[54:57]
	s_barrier
	s_add_i32 s45, s45, 2
	s_add_u32 s22, s22, 0x100
	s_addc_u32 s23, s23, 0
	s_add_u32 s5, s5, 0x100
	s_addc_u32 s15, s15, 0
	s_cmp_gt_u32 s45, 29
	s_cbranch_scc0 .LBB0_704
	s_setprio 0
	s_and_b64 vcc, exec, s[12:13]
	s_cbranch_vccz .LBB0_707
	s_barrier

.Lsp_p5:
.LBB0_842:
	v_add_u32_e32 v158, s36, v152
	v_add_u32_e32 v162, s37, v152
	ds_read_b128 v[142:145], v158
	ds_read_b128 v[146:149], v158 offset:1024
	ds_read_b128 v[154:157], v158 offset:2048
	ds_read_b128 v[158:161], v158 offset:3072
	ds_read_b128 v[166:169], v162
	ds_read_b128 v[170:173], v162 offset:1024
	ds_read_b128 v[174:177], v162 offset:2048
	ds_read_b128 v[178:181], v162 offset:3072
	s_add_i32 s49, s20, 2
	s_add_u32 s21, s4, 0xfffa0080
	s_addc_u32 s22, s5, -1
	s_cmp_eq_u32 s46, s20
	s_cselect_b32 s20, s16, s47
	s_cselect_b32 s23, s15, s22
	s_cselect_b32 s22, s14, s21
	s_cselect_b32 s21, s17, s48
	v_lshl_add_u64 v[162:163], s[4:5], 0, v[138:139]
	s_add_i32 m0, s26, 0xc000
	ds_read_b128 v[182:185], v153
	ds_read_b128 v[186:189], v153 offset:1024
	ds_read_b128 v[190:193], v153 offset:2048
	ds_read_b128 v[194:197], v153 offset:3072
	ds_read_b128 v[198:201], v153 offset:4096
	ds_read_b128 v[202:205], v153 offset:5120
	ds_read_b128 v[206:209], v153 offset:6144
	ds_read_b128 v[210:213], v153 offset:7168
	global_load_lds_dwordx4 v[162:163], off
	v_lshl_add_u64 v[162:163], s[4:5], 0, v[140:141]
	s_add_i32 m0, s26, 0xe000
	s_nop 0
	global_load_lds_dwordx4 v[162:163], off
	s_waitcnt vmcnt(8)
	s_waitcnt lgkmcnt(0)
	s_barrier
	v_mfma_f32_16x16x32_bf16 v[126:129], v[142:145], v[182:185], v[126:129]
	v_mfma_f32_16x16x32_bf16 v[122:125], v[154:157], v[182:185], v[122:125]
	v_mfma_f32_16x16x32_bf16 v[114:117], v[154:157], v[190:193], v[114:117]
	v_mfma_f32_16x16x32_bf16 v[118:121], v[142:145], v[190:193], v[118:121]
	v_mfma_f32_16x16x32_bf16 v[110:113], v[142:145], v[198:201], v[110:113]
	v_mfma_f32_16x16x32_bf16 v[106:109], v[154:157], v[198:201], v[106:109]
	v_mfma_f32_16x16x32_bf16 v[98:101], v[154:157], v[206:209], v[98:101]
	v_mfma_f32_16x16x32_bf16 v[102:105], v[142:145], v[206:209], v[102:105]
	v_mfma_f32_16x16x32_bf16 v[70:73], v[166:169], v[206:209], v[70:73]
	v_mfma_f32_16x16x32_bf16 v[66:69], v[174:177], v[206:209], v[66:69]
	v_mfma_f32_16x16x32_bf16 v[74:77], v[174:177], v[198:201], v[74:77]
	v_mfma_f32_16x16x32_bf16 v[78:81], v[166:169], v[198:201], v[78:81]
	v_mfma_f32_16x16x32_bf16 v[86:89], v[166:169], v[190:193], v[86:89]
	v_mfma_f32_16x16x32_bf16 v[82:85], v[174:177], v[190:193], v[82:85]
	v_mfma_f32_16x16x32_bf16 v[90:93], v[174:177], v[182:185], v[90:93]
	v_mfma_f32_16x16x32_bf16 v[94:97], v[166:169], v[182:185], v[94:97]
	v_mfma_f32_16x16x32_bf16 v[126:129], v[146:149], v[186:189], v[126:129]
	v_mfma_f32_16x16x32_bf16 v[122:125], v[158:161], v[186:189], v[122:125]
	v_mfma_f32_16x16x32_bf16 v[114:117], v[158:161], v[194:197], v[114:117]
	v_mfma_f32_16x16x32_bf16 v[118:121], v[146:149], v[194:197], v[118:121]
	v_mfma_f32_16x16x32_bf16 v[110:113], v[146:149], v[202:205], v[110:113]
	v_mfma_f32_16x16x32_bf16 v[106:109], v[158:161], v[202:205], v[106:109]
	v_mfma_f32_16x16x32_bf16 v[98:101], v[158:161], v[210:213], v[98:101]
	v_mfma_f32_16x16x32_bf16 v[102:105], v[146:149], v[210:213], v[102:105]
	v_mfma_f32_16x16x32_bf16 v[70:73], v[170:173], v[210:213], v[70:73]
	v_mfma_f32_16x16x32_bf16 v[66:69], v[178:181], v[210:213], v[66:69]
	v_mfma_f32_16x16x32_bf16 v[74:77], v[178:181], v[202:205], v[74:77]
	v_mfma_f32_16x16x32_bf16 v[78:81], v[170:173], v[202:205], v[78:81]
	v_mfma_f32_16x16x32_bf16 v[86:89], v[170:173], v[194:197], v[86:89]
	v_mfma_f32_16x16x32_bf16 v[82:85], v[178:181], v[194:197], v[82:85]
	v_mfma_f32_16x16x32_bf16 v[90:93], v[178:181], v[186:189], v[90:93]
	v_mfma_f32_16x16x32_bf16 v[94:97], v[170:173], v[186:189], v[94:97]
	s_barrier
	s_add_i32 s50, s36, s25
	v_lshl_add_u64 v[162:163], s[20:21], 0, v[132:133]
	s_mov_b32 m0, s50
	ds_read_b128 v[182:185], v153 offset:16384
	ds_read_b128 v[186:189], v153 offset:17408
	ds_read_b128 v[190:193], v153 offset:18432
	ds_read_b128 v[194:197], v153 offset:19456
	ds_read_b128 v[198:201], v153 offset:20480
	ds_read_b128 v[202:205], v153 offset:21504
	ds_read_b128 v[206:209], v153 offset:22528
	ds_read_b128 v[210:213], v153 offset:23552
	global_load_lds_dwordx4 v[162:163], off
	s_add_i32 m0, s50, 0x2000
	s_add_u32 s50, s20, 0x60000
	v_lshl_add_u64 v[214:215], s[20:21], 0, v[136:137]
	s_addc_u32 s51, s21, 0
	s_add_i32 s52, s37, s25
	global_load_lds_dwordx4 v[214:215], off
	v_lshl_add_u64 v[216:217], s[50:51], 0, v[132:133]
	s_mov_b32 m0, s52
	v_lshl_add_u64 v[218:219], s[22:23], 0, v[134:135]
	global_load_lds_dwordx4 v[216:217], off
	v_lshl_add_u64 v[216:217], s[50:51], 0, v[136:137]
	s_add_i32 m0, s52, 0x2000
	s_nop 0
	global_load_lds_dwordx4 v[216:217], off
	v_lshl_add_u64 v[216:217], s[22:23], 0, v[130:131]
	s_mov_b32 m0, s26
	s_nop 0
	global_load_lds_dwordx4 v[216:217], off
	s_mov_b32 m0, s27
	s_nop 0
	global_load_lds_dwordx4 v[218:219], off
	s_waitcnt vmcnt(8)
	s_waitcnt lgkmcnt(0)
	s_barrier
	v_mfma_f32_16x16x32_bf16 v[62:65], v[142:145], v[182:185], v[62:65]
	v_mfma_f32_16x16x32_bf16 v[58:61], v[154:157], v[182:185], v[58:61]
	v_mfma_f32_16x16x32_bf16 v[50:53], v[154:157], v[190:193], v[50:53]
	v_mfma_f32_16x16x32_bf16 v[54:57], v[142:145], v[190:193], v[54:57]
	v_mfma_f32_16x16x32_bf16 v[46:49], v[142:145], v[198:201], v[46:49]
	v_mfma_f32_16x16x32_bf16 v[42:45], v[154:157], v[198:201], v[42:45]
	v_mfma_f32_16x16x32_bf16 v[34:37], v[154:157], v[206:209], v[34:37]
	v_mfma_f32_16x16x32_bf16 v[38:41], v[142:145], v[206:209], v[38:41]
	v_mfma_f32_16x16x32_bf16 v[6:9], v[166:169], v[206:209], v[6:9]
	v_mfma_f32_16x16x32_bf16 v[2:5], v[174:177], v[206:209], v[2:5]
	v_mfma_f32_16x16x32_bf16 v[10:13], v[174:177], v[198:201], v[10:13]
	v_mfma_f32_16x16x32_bf16 v[14:17], v[166:169], v[198:201], v[14:17]
	v_mfma_f32_16x16x32_bf16 v[22:25], v[166:169], v[190:193], v[22:25]
	v_mfma_f32_16x16x32_bf16 v[18:21], v[174:177], v[190:193], v[18:21]
	v_mfma_f32_16x16x32_bf16 v[26:29], v[174:177], v[182:185], v[26:29]
	v_mfma_f32_16x16x32_bf16 v[30:33], v[166:169], v[182:185], v[30:33]
	v_mfma_f32_16x16x32_bf16 v[62:65], v[146:149], v[186:189], v[62:65]
	v_mfma_f32_16x16x32_bf16 v[58:61], v[158:161], v[186:189], v[58:61]
	v_mfma_f32_16x16x32_bf16 v[50:53], v[158:161], v[194:197], v[50:53]
	v_mfma_f32_16x16x32_bf16 v[54:57], v[146:149], v[194:197], v[54:57]
	v_mfma_f32_16x16x32_bf16 v[46:49], v[146:149], v[202:205], v[46:49]
	v_mfma_f32_16x16x32_bf16 v[42:45], v[158:161], v[202:205], v[42:45]
	v_mfma_f32_16x16x32_bf16 v[34:37], v[158:161], v[210:213], v[34:37]
	v_mfma_f32_16x16x32_bf16 v[38:41], v[146:149], v[210:213], v[38:41]
	v_mfma_f32_16x16x32_bf16 v[6:9], v[170:173], v[210:213], v[6:9]
	v_mfma_f32_16x16x32_bf16 v[2:5], v[178:181], v[210:213], v[2:5]
	v_mfma_f32_16x16x32_bf16 v[10:13], v[178:181], v[202:205], v[10:13]
	v_mfma_f32_16x16x32_bf16 v[14:17], v[170:173], v[202:205], v[14:17]
	v_mfma_f32_16x16x32_bf16 v[22:25], v[170:173], v[194:197], v[22:25]
	v_mfma_f32_16x16x32_bf16 v[18:21], v[178:181], v[194:197], v[18:21]
	v_mfma_f32_16x16x32_bf16 v[26:29], v[178:181], v[186:189], v[26:29]
	v_mfma_f32_16x16x32_bf16 v[30:33], v[170:173], v[186:189], v[30:33]
	s_barrier
	s_add_i32 s50, 0, 0x18000
	s_add_i32 s51, 0, 0x1c000
	v_add_u32_e32 v158, s50, v152
	v_add_u32_e32 v164, s51, v152
	ds_read_b128 v[142:145], v158
	ds_read_b128 v[146:149], v158 offset:1024
	ds_read_b128 v[154:157], v158 offset:2048
	ds_read_b128 v[158:161], v158 offset:3072
	ds_read_b128 v[166:169], v164
	ds_read_b128 v[170:173], v164 offset:1024
	ds_read_b128 v[174:177], v164 offset:2048
	ds_read_b128 v[178:181], v164 offset:3072
	s_add_u32 s22, s22, 0x60000
	s_addc_u32 s23, s23, 0
	s_mov_b32 m0, s28
	v_lshl_add_u64 v[220:221], s[22:23], 0, v[130:131]
	ds_read_b128 v[182:185], v153 offset:32768
	ds_read_b128 v[186:189], v153 offset:33792
	ds_read_b128 v[190:193], v153 offset:34816
	ds_read_b128 v[194:197], v153 offset:35840
	ds_read_b128 v[198:201], v153 offset:36864
	ds_read_b128 v[202:205], v153 offset:37888
	ds_read_b128 v[206:209], v153 offset:38912
	ds_read_b128 v[210:213], v153 offset:39936
	global_load_lds_dwordx4 v[220:221], off
	v_lshl_add_u64 v[220:221], s[22:23], 0, v[134:135]
	s_mov_b32 m0, s29
	s_nop 0
	global_load_lds_dwordx4 v[220:221], off
	s_waitcnt vmcnt(8)
	s_waitcnt lgkmcnt(0)
	s_barrier
	v_mfma_f32_16x16x32_bf16 v[126:129], v[142:145], v[182:185], v[126:129]
	v_mfma_f32_16x16x32_bf16 v[122:125], v[154:157], v[182:185], v[122:125]
	v_mfma_f32_16x16x32_bf16 v[114:117], v[154:157], v[190:193], v[114:117]
	v_mfma_f32_16x16x32_bf16 v[118:121], v[142:145], v[190:193], v[118:121]
	v_mfma_f32_16x16x32_bf16 v[110:113], v[142:145], v[198:201], v[110:113]
	v_mfma_f32_16x16x32_bf16 v[106:109], v[154:157], v[198:201], v[106:109]
	v_mfma_f32_16x16x32_bf16 v[98:101], v[154:157], v[206:209], v[98:101]
	v_mfma_f32_16x16x32_bf16 v[102:105], v[142:145], v[206:209], v[102:105]
	v_mfma_f32_16x16x32_bf16 v[70:73], v[166:169], v[206:209], v[70:73]
	v_mfma_f32_16x16x32_bf16 v[66:69], v[174:177], v[206:209], v[66:69]
	v_mfma_f32_16x16x32_bf16 v[74:77], v[174:177], v[198:201], v[74:77]
	v_mfma_f32_16x16x32_bf16 v[78:81], v[166:169], v[198:201], v[78:81]
	v_mfma_f32_16x16x32_bf16 v[86:89], v[166:169], v[190:193], v[86:89]
	v_mfma_f32_16x16x32_bf16 v[82:85], v[174:177], v[190:193], v[82:85]
	v_mfma_f32_16x16x32_bf16 v[90:93], v[174:177], v[182:185], v[90:93]
	v_mfma_f32_16x16x32_bf16 v[94:97], v[166:169], v[182:185], v[94:97]
	v_mfma_f32_16x16x32_bf16 v[126:129], v[146:149], v[186:189], v[126:129]
	v_mfma_f32_16x16x32_bf16 v[122:125], v[158:161], v[186:189], v[122:125]
	v_mfma_f32_16x16x32_bf16 v[114:117], v[158:161], v[194:197], v[114:117]
	v_mfma_f32_16x16x32_bf16 v[118:121], v[146:149], v[194:197], v[118:121]
	v_mfma_f32_16x16x32_bf16 v[110:113], v[146:149], v[202:205], v[110:113]
	v_mfma_f32_16x16x32_bf16 v[106:109], v[158:161], v[202:205], v[106:109]
	v_mfma_f32_16x16x32_bf16 v[98:101], v[158:161], v[210:213], v[98:101]
	v_mfma_f32_16x16x32_bf16 v[102:105], v[146:149], v[210:213], v[102:105]
	v_mfma_f32_16x16x32_bf16 v[70:73], v[170:173], v[210:213], v[70:73]
	v_mfma_f32_16x16x32_bf16 v[66:69], v[178:181], v[210:213], v[66:69]
	v_mfma_f32_16x16x32_bf16 v[74:77], v[178:181], v[202:205], v[74:77]
	v_mfma_f32_16x16x32_bf16 v[78:81], v[170:173], v[202:205], v[78:81]
	v_mfma_f32_16x16x32_bf16 v[86:89], v[170:173], v[194:197], v[86:89]
	v_mfma_f32_16x16x32_bf16 v[82:85], v[178:181], v[194:197], v[82:85]
	v_mfma_f32_16x16x32_bf16 v[90:93], v[178:181], v[186:189], v[90:93]
	v_mfma_f32_16x16x32_bf16 v[94:97], v[170:173], v[186:189], v[94:97]
	s_barrier
	s_add_i32 s22, s50, s25
	v_lshl_add_u64 v[162:163], v[162:163], 0, s[8:9]
	s_mov_b32 m0, s22
	ds_read_b128 v[182:185], v153 offset:49152
	ds_read_b128 v[186:189], v153 offset:50176
	ds_read_b128 v[190:193], v153 offset:51200
	ds_read_b128 v[194:197], v153 offset:52224
	ds_read_b128 v[198:201], v153 offset:53248
	ds_read_b128 v[202:205], v153 offset:54272
	ds_read_b128 v[206:209], v153 offset:55296
	ds_read_b128 v[210:213], v153 offset:56320
	global_load_lds_dwordx4 v[162:163], off
	s_add_i32 m0, s22, 0x2000
	s_add_u32 s20, s20, 0x60080
	v_lshl_add_u64 v[162:163], v[214:215], 0, s[8:9]
	s_addc_u32 s21, s21, 0
	s_add_i32 s22, s51, s25
	global_load_lds_dwordx4 v[162:163], off
	v_lshl_add_u64 v[162:163], s[20:21], 0, v[132:133]
	s_mov_b32 m0, s22
	s_nop 0
	global_load_lds_dwordx4 v[162:163], off
	v_lshl_add_u64 v[162:163], s[20:21], 0, v[136:137]
	s_add_i32 m0, s22, 0x2000
	s_nop 0
	global_load_lds_dwordx4 v[162:163], off
	v_lshl_add_u64 v[162:163], v[216:217], 0, s[8:9]
	s_mov_b32 m0, s34
	s_nop 0
	global_load_lds_dwordx4 v[162:163], off
	v_lshl_add_u64 v[162:163], v[218:219], 0, s[8:9]
	s_mov_b32 m0, s35
	s_nop 0
	global_load_lds_dwordx4 v[162:163], off
	s_waitcnt vmcnt(8)
	s_waitcnt lgkmcnt(0)
	s_barrier
	v_mfma_f32_16x16x32_bf16 v[62:65], v[142:145], v[182:185], v[62:65]
	v_mfma_f32_16x16x32_bf16 v[58:61], v[154:157], v[182:185], v[58:61]
	v_mfma_f32_16x16x32_bf16 v[50:53], v[154:157], v[190:193], v[50:53]
	v_mfma_f32_16x16x32_bf16 v[54:57], v[142:145], v[190:193], v[54:57]
	v_mfma_f32_16x16x32_bf16 v[46:49], v[142:145], v[198:201], v[46:49]
	v_mfma_f32_16x16x32_bf16 v[42:45], v[154:157], v[198:201], v[42:45]
	v_mfma_f32_16x16x32_bf16 v[34:37], v[154:157], v[206:209], v[34:37]
	v_mfma_f32_16x16x32_bf16 v[38:41], v[142:145], v[206:209], v[38:41]
	v_mfma_f32_16x16x32_bf16 v[6:9], v[166:169], v[206:209], v[6:9]
	v_mfma_f32_16x16x32_bf16 v[2:5], v[174:177], v[206:209], v[2:5]
	v_mfma_f32_16x16x32_bf16 v[10:13], v[174:177], v[198:201], v[10:13]
	v_mfma_f32_16x16x32_bf16 v[14:17], v[166:169], v[198:201], v[14:17]
	v_mfma_f32_16x16x32_bf16 v[22:25], v[166:169], v[190:193], v[22:25]
	v_mfma_f32_16x16x32_bf16 v[18:21], v[174:177], v[190:193], v[18:21]
	v_mfma_f32_16x16x32_bf16 v[26:29], v[174:177], v[182:185], v[26:29]
	v_mfma_f32_16x16x32_bf16 v[30:33], v[166:169], v[182:185], v[30:33]
	v_mfma_f32_16x16x32_bf16 v[62:65], v[146:149], v[186:189], v[62:65]
	v_mfma_f32_16x16x32_bf16 v[58:61], v[158:161], v[186:189], v[58:61]
	v_mfma_f32_16x16x32_bf16 v[50:53], v[158:161], v[194:197], v[50:53]
	v_mfma_f32_16x16x32_bf16 v[54:57], v[146:149], v[194:197], v[54:57]
	v_mfma_f32_16x16x32_bf16 v[46:49], v[146:149], v[202:205], v[46:49]
	v_mfma_f32_16x16x32_bf16 v[42:45], v[158:161], v[202:205], v[42:45]
	v_mfma_f32_16x16x32_bf16 v[34:37], v[158:161], v[210:213], v[34:37]
	v_mfma_f32_16x16x32_bf16 v[38:41], v[146:149], v[210:213], v[38:41]
	v_mfma_f32_16x16x32_bf16 v[6:9], v[170:173], v[210:213], v[6:9]
	v_mfma_f32_16x16x32_bf16 v[2:5], v[178:181], v[210:213], v[2:5]
	v_mfma_f32_16x16x32_bf16 v[10:13], v[178:181], v[202:205], v[10:13]
	v_mfma_f32_16x16x32_bf16 v[14:17], v[170:173], v[202:205], v[14:17]
	v_mfma_f32_16x16x32_bf16 v[22:25], v[170:173], v[194:197], v[22:25]
	v_mfma_f32_16x16x32_bf16 v[18:21], v[178:181], v[194:197], v[18:21]
	v_mfma_f32_16x16x32_bf16 v[26:29], v[178:181], v[186:189], v[26:29]
	v_mfma_f32_16x16x32_bf16 v[30:33], v[170:173], v[186:189], v[30:33]
	s_barrier
	s_add_u32 s4, s4, 0x100
	s_addc_u32 s5, s5, 0
	s_add_u32 s47, s47, 0x100
	s_addc_u32 s48, s48, 0
	s_cmp_ge_i32 s49, s45
	s_mov_b32 s20, s49
	s_cbranch_scc0 .LBB0_842
	s_setprio 0
	s_and_b64 vcc, exec, s[10:11]
	s_cbranch_vccz .LBB0_845
	s_barrier

.Lsp_p6:
.LBB0_1019:
	ds_read_b128 v[142:145], v149
	ds_read_b128 v[154:157], v149 offset:1024
	ds_read_b128 v[158:161], v149 offset:2048
	ds_read_b128 v[166:169], v149 offset:3072
	ds_read_b128 v[170:173], v150
	ds_read_b128 v[174:177], v150 offset:1024
	ds_read_b128 v[178:181], v150 offset:2048
	ds_read_b128 v[182:185], v150 offset:3072
	s_add_u32 s28, s26, 0xfff80080
	s_addc_u32 s29, s27, -1
	s_cmp_eq_u32 s49, 28
	s_cselect_b32 s31, s1, s29
	s_cselect_b32 s30, s15, s28
	s_cselect_b32 s29, s17, s48
	s_cselect_b32 s28, s46, s47
	v_lshl_add_u64 v[162:163], s[26:27], 0, v[138:139]
	s_add_i32 m0, s34, 0xc000
	ds_read_b128 v[186:189], v151
	ds_read_b128 v[190:193], v151 offset:1024
	ds_read_b128 v[194:197], v151 offset:2048
	ds_read_b128 v[198:201], v151 offset:3072
	ds_read_b128 v[202:205], v151 offset:4096
	ds_read_b128 v[206:209], v151 offset:5120
	ds_read_b128 v[210:213], v151 offset:6144
	ds_read_b128 v[214:217], v151 offset:7168
	global_load_lds_dwordx4 v[162:163], off
	v_lshl_add_u64 v[162:163], s[26:27], 0, v[140:141]
	s_add_i32 m0, s34, 0xe000
	s_nop 0
	global_load_lds_dwordx4 v[162:163], off
	s_waitcnt vmcnt(8)
	s_waitcnt lgkmcnt(0)
	s_barrier
	v_mfma_f32_16x16x32_bf16 v[126:129], v[142:145], v[186:189], v[126:129]
	v_mfma_f32_16x16x32_bf16 v[122:125], v[158:161], v[186:189], v[122:125]
	v_mfma_f32_16x16x32_bf16 v[106:109], v[158:161], v[194:197], v[106:109]
	v_mfma_f32_16x16x32_bf16 v[110:113], v[142:145], v[194:197], v[110:113]
	v_mfma_f32_16x16x32_bf16 v[94:97], v[142:145], v[202:205], v[94:97]
	v_mfma_f32_16x16x32_bf16 v[90:93], v[158:161], v[202:205], v[90:93]
	v_mfma_f32_16x16x32_bf16 v[74:77], v[158:161], v[210:213], v[74:77]
	v_mfma_f32_16x16x32_bf16 v[78:81], v[142:145], v[210:213], v[78:81]
	v_mfma_f32_16x16x32_bf16 v[70:73], v[170:173], v[210:213], v[70:73]
	v_mfma_f32_16x16x32_bf16 v[66:69], v[178:181], v[210:213], v[66:69]
	v_mfma_f32_16x16x32_bf16 v[82:85], v[178:181], v[202:205], v[82:85]
	v_mfma_f32_16x16x32_bf16 v[86:89], v[170:173], v[202:205], v[86:89]
	v_mfma_f32_16x16x32_bf16 v[102:105], v[170:173], v[194:197], v[102:105]
	v_mfma_f32_16x16x32_bf16 v[98:101], v[178:181], v[194:197], v[98:101]
	v_mfma_f32_16x16x32_bf16 v[114:117], v[178:181], v[186:189], v[114:117]
	v_mfma_f32_16x16x32_bf16 v[118:121], v[170:173], v[186:189], v[118:121]
	v_mfma_f32_16x16x32_bf16 v[126:129], v[154:157], v[190:193], v[126:129]
	v_mfma_f32_16x16x32_bf16 v[122:125], v[166:169], v[190:193], v[122:125]
	v_mfma_f32_16x16x32_bf16 v[106:109], v[166:169], v[198:201], v[106:109]
	v_mfma_f32_16x16x32_bf16 v[110:113], v[154:157], v[198:201], v[110:113]
	v_mfma_f32_16x16x32_bf16 v[94:97], v[154:157], v[206:209], v[94:97]
	v_mfma_f32_16x16x32_bf16 v[90:93], v[166:169], v[206:209], v[90:93]
	v_mfma_f32_16x16x32_bf16 v[74:77], v[166:169], v[214:217], v[74:77]
	v_mfma_f32_16x16x32_bf16 v[78:81], v[154:157], v[214:217], v[78:81]
	v_mfma_f32_16x16x32_bf16 v[70:73], v[174:177], v[214:217], v[70:73]
	v_mfma_f32_16x16x32_bf16 v[66:69], v[182:185], v[214:217], v[66:69]
	v_mfma_f32_16x16x32_bf16 v[82:85], v[182:185], v[206:209], v[82:85]
	v_mfma_f32_16x16x32_bf16 v[86:89], v[174:177], v[206:209], v[86:89]
	v_mfma_f32_16x16x32_bf16 v[102:105], v[174:177], v[198:201], v[102:105]
	v_mfma_f32_16x16x32_bf16 v[98:101], v[182:185], v[198:201], v[98:101]
	v_mfma_f32_16x16x32_bf16 v[114:117], v[182:185], v[190:193], v[114:117]
	v_mfma_f32_16x16x32_bf16 v[118:121], v[174:177], v[190:193], v[118:121]
	s_barrier
	s_add_i32 s50, s44, s25
	v_lshl_add_u64 v[162:163], s[28:29], 0, v[132:133]
	s_mov_b32 m0, s50
	ds_read_b128 v[186:189], v151 offset:16384
	ds_read_b128 v[190:193], v151 offset:17408
	ds_read_b128 v[194:197], v151 offset:18432
	ds_read_b128 v[198:201], v151 offset:19456
	ds_read_b128 v[202:205], v151 offset:20480
	ds_read_b128 v[206:209], v151 offset:21504
	ds_read_b128 v[210:213], v151 offset:22528
	ds_read_b128 v[214:217], v151 offset:23552
	global_load_lds_dwordx4 v[162:163], off
	s_add_i32 m0, s50, 0x2000
	s_add_u32 s50, s28, 0x80000
	v_lshl_add_u64 v[218:219], s[28:29], 0, v[136:137]
	s_addc_u32 s51, s29, 0
	s_add_i32 s52, s45, s25
	global_load_lds_dwordx4 v[218:219], off
	v_lshl_add_u64 v[220:221], s[50:51], 0, v[132:133]
	s_mov_b32 m0, s52
	v_lshl_add_u64 v[222:223], s[30:31], 0, v[134:135]
	global_load_lds_dwordx4 v[220:221], off
	v_lshl_add_u64 v[220:221], s[50:51], 0, v[136:137]
	s_add_i32 m0, s52, 0x2000
	s_nop 0
	global_load_lds_dwordx4 v[220:221], off
	v_lshl_add_u64 v[220:221], s[30:31], 0, v[130:131]
	s_mov_b32 m0, s34
	s_nop 0
	global_load_lds_dwordx4 v[220:221], off
	s_mov_b32 m0, s35
	s_nop 0
	global_load_lds_dwordx4 v[222:223], off
	s_waitcnt vmcnt(8)
	s_waitcnt lgkmcnt(0)
	s_barrier
	v_mfma_f32_16x16x32_bf16 v[62:65], v[142:145], v[186:189], v[62:65]
	v_mfma_f32_16x16x32_bf16 v[58:61], v[158:161], v[186:189], v[58:61]
	v_mfma_f32_16x16x32_bf16 v[42:45], v[158:161], v[194:197], v[42:45]
	v_mfma_f32_16x16x32_bf16 v[46:49], v[142:145], v[194:197], v[46:49]
	v_mfma_f32_16x16x32_bf16 v[30:33], v[142:145], v[202:205], v[30:33]
	v_mfma_f32_16x16x32_bf16 v[26:29], v[158:161], v[202:205], v[26:29]
	v_mfma_f32_16x16x32_bf16 v[10:13], v[158:161], v[210:213], v[10:13]
	v_mfma_f32_16x16x32_bf16 v[14:17], v[142:145], v[210:213], v[14:17]
	v_mfma_f32_16x16x32_bf16 v[6:9], v[170:173], v[210:213], v[6:9]
	v_mfma_f32_16x16x32_bf16 v[2:5], v[178:181], v[210:213], v[2:5]
	v_mfma_f32_16x16x32_bf16 v[18:21], v[178:181], v[202:205], v[18:21]
	v_mfma_f32_16x16x32_bf16 v[22:25], v[170:173], v[202:205], v[22:25]
	v_mfma_f32_16x16x32_bf16 v[38:41], v[170:173], v[194:197], v[38:41]
	v_mfma_f32_16x16x32_bf16 v[34:37], v[178:181], v[194:197], v[34:37]
	v_mfma_f32_16x16x32_bf16 v[50:53], v[178:181], v[186:189], v[50:53]
	v_mfma_f32_16x16x32_bf16 v[54:57], v[170:173], v[186:189], v[54:57]
	v_mfma_f32_16x16x32_bf16 v[62:65], v[154:157], v[190:193], v[62:65]
	v_mfma_f32_16x16x32_bf16 v[58:61], v[166:169], v[190:193], v[58:61]
	v_mfma_f32_16x16x32_bf16 v[42:45], v[166:169], v[198:201], v[42:45]
	v_mfma_f32_16x16x32_bf16 v[46:49], v[154:157], v[198:201], v[46:49]
	v_mfma_f32_16x16x32_bf16 v[30:33], v[154:157], v[206:209], v[30:33]
	v_mfma_f32_16x16x32_bf16 v[26:29], v[166:169], v[206:209], v[26:29]
	v_mfma_f32_16x16x32_bf16 v[10:13], v[166:169], v[214:217], v[10:13]
	v_mfma_f32_16x16x32_bf16 v[14:17], v[154:157], v[214:217], v[14:17]
	v_mfma_f32_16x16x32_bf16 v[6:9], v[174:177], v[214:217], v[6:9]
	v_mfma_f32_16x16x32_bf16 v[2:5], v[182:185], v[214:217], v[2:5]
	v_mfma_f32_16x16x32_bf16 v[18:21], v[182:185], v[206:209], v[18:21]
	v_mfma_f32_16x16x32_bf16 v[22:25], v[174:177], v[206:209], v[22:25]
	v_mfma_f32_16x16x32_bf16 v[38:41], v[174:177], v[198:201], v[38:41]
	v_mfma_f32_16x16x32_bf16 v[34:37], v[182:185], v[198:201], v[34:37]
	v_mfma_f32_16x16x32_bf16 v[50:53], v[182:185], v[190:193], v[50:53]
	v_mfma_f32_16x16x32_bf16 v[54:57], v[174:177], v[190:193], v[54:57]
	s_barrier
	s_add_i32 s50, 0, 0x18000
	v_add_u32_e32 v153, s50, v148
	s_add_i32 s51, 0, 0x1c000
	ds_read_b128 v[142:145], v153
	ds_read_b128 v[154:157], v153 offset:1024
	ds_read_b128 v[158:161], v153 offset:2048
	ds_read_b128 v[166:169], v153 offset:3072
	v_add_u32_e32 v153, s51, v148
	ds_read_b128 v[170:173], v153
	ds_read_b128 v[174:177], v153 offset:1024
	ds_read_b128 v[178:181], v153 offset:2048
	ds_read_b128 v[182:185], v153 offset:3072
	s_add_u32 s30, s30, 0x80000
	s_addc_u32 s31, s31, 0
	s_mov_b32 m0, s36
	v_lshl_add_u64 v[224:225], s[30:31], 0, v[130:131]
	ds_read_b128 v[186:189], v151 offset:32768
	ds_read_b128 v[190:193], v151 offset:33792
	ds_read_b128 v[194:197], v151 offset:34816
	ds_read_b128 v[198:201], v151 offset:35840
	ds_read_b128 v[202:205], v151 offset:36864
	ds_read_b128 v[206:209], v151 offset:37888
	ds_read_b128 v[210:213], v151 offset:38912
	ds_read_b128 v[214:217], v151 offset:39936
	global_load_lds_dwordx4 v[224:225], off
	v_lshl_add_u64 v[224:225], s[30:31], 0, v[134:135]
	s_mov_b32 m0, s37
	s_nop 0
	global_load_lds_dwordx4 v[224:225], off
	s_waitcnt vmcnt(8)
	s_waitcnt lgkmcnt(0)
	s_barrier
	v_mfma_f32_16x16x32_bf16 v[126:129], v[142:145], v[186:189], v[126:129]
	v_mfma_f32_16x16x32_bf16 v[122:125], v[158:161], v[186:189], v[122:125]
	v_mfma_f32_16x16x32_bf16 v[106:109], v[158:161], v[194:197], v[106:109]
	v_mfma_f32_16x16x32_bf16 v[110:113], v[142:145], v[194:197], v[110:113]
	v_mfma_f32_16x16x32_bf16 v[94:97], v[142:145], v[202:205], v[94:97]
	v_mfma_f32_16x16x32_bf16 v[90:93], v[158:161], v[202:205], v[90:93]
	v_mfma_f32_16x16x32_bf16 v[74:77], v[158:161], v[210:213], v[74:77]
	v_mfma_f32_16x16x32_bf16 v[78:81], v[142:145], v[210:213], v[78:81]
	v_mfma_f32_16x16x32_bf16 v[70:73], v[170:173], v[210:213], v[70:73]
	v_mfma_f32_16x16x32_bf16 v[66:69], v[178:181], v[210:213], v[66:69]
	v_mfma_f32_16x16x32_bf16 v[82:85], v[178:181], v[202:205], v[82:85]
	v_mfma_f32_16x16x32_bf16 v[86:89], v[170:173], v[202:205], v[86:89]
	v_mfma_f32_16x16x32_bf16 v[102:105], v[170:173], v[194:197], v[102:105]
	v_mfma_f32_16x16x32_bf16 v[98:101], v[178:181], v[194:197], v[98:101]
	v_mfma_f32_16x16x32_bf16 v[114:117], v[178:181], v[186:189], v[114:117]
	v_mfma_f32_16x16x32_bf16 v[118:121], v[170:173], v[186:189], v[118:121]
	v_mfma_f32_16x16x32_bf16 v[126:129], v[154:157], v[190:193], v[126:129]
	v_mfma_f32_16x16x32_bf16 v[122:125], v[166:169], v[190:193], v[122:125]
	v_mfma_f32_16x16x32_bf16 v[106:109], v[166:169], v[198:201], v[106:109]
	v_mfma_f32_16x16x32_bf16 v[110:113], v[154:157], v[198:201], v[110:113]
	v_mfma_f32_16x16x32_bf16 v[94:97], v[154:157], v[206:209], v[94:97]
	v_mfma_f32_16x16x32_bf16 v[90:93], v[166:169], v[206:209], v[90:93]
	v_mfma_f32_16x16x32_bf16 v[74:77], v[166:169], v[214:217], v[74:77]
	v_mfma_f32_16x16x32_bf16 v[78:81], v[154:157], v[214:217], v[78:81]
	v_mfma_f32_16x16x32_bf16 v[70:73], v[174:177], v[214:217], v[70:73]
	v_mfma_f32_16x16x32_bf16 v[66:69], v[182:185], v[214:217], v[66:69]
	v_mfma_f32_16x16x32_bf16 v[82:85], v[182:185], v[206:209], v[82:85]
	v_mfma_f32_16x16x32_bf16 v[86:89], v[174:177], v[206:209], v[86:89]
	v_mfma_f32_16x16x32_bf16 v[102:105], v[174:177], v[198:201], v[102:105]
	v_mfma_f32_16x16x32_bf16 v[98:101], v[182:185], v[198:201], v[98:101]
	v_mfma_f32_16x16x32_bf16 v[114:117], v[182:185], v[190:193], v[114:117]
	v_mfma_f32_16x16x32_bf16 v[118:121], v[174:177], v[190:193], v[118:121]
	s_barrier
	s_add_i32 s30, s50, s25
	v_lshl_add_u64 v[162:163], v[162:163], 0, s[8:9]
	s_mov_b32 m0, s30
	ds_read_b128 v[186:189], v151 offset:49152
	ds_read_b128 v[190:193], v151 offset:50176
	ds_read_b128 v[194:197], v151 offset:51200
	ds_read_b128 v[198:201], v151 offset:52224
	ds_read_b128 v[202:205], v151 offset:53248
	ds_read_b128 v[206:209], v151 offset:54272
	ds_read_b128 v[210:213], v151 offset:55296
	ds_read_b128 v[214:217], v151 offset:56320
	global_load_lds_dwordx4 v[162:163], off
	s_add_i32 m0, s30, 0x2000
	s_add_u32 s28, s28, 0x80080
	v_lshl_add_u64 v[162:163], v[218:219], 0, s[8:9]
	s_addc_u32 s29, s29, 0
	s_add_i32 s30, s51, s25
	global_load_lds_dwordx4 v[162:163], off
	v_lshl_add_u64 v[162:163], s[28:29], 0, v[132:133]
	s_mov_b32 m0, s30
	s_nop 0
	global_load_lds_dwordx4 v[162:163], off
	v_lshl_add_u64 v[162:163], s[28:29], 0, v[136:137]
	s_add_i32 m0, s30, 0x2000
	s_nop 0
	global_load_lds_dwordx4 v[162:163], off
	v_lshl_add_u64 v[162:163], v[220:221], 0, s[8:9]
	s_mov_b32 m0, s41
	s_nop 0
	global_load_lds_dwordx4 v[162:163], off
	v_lshl_add_u64 v[162:163], v[222:223], 0, s[8:9]
	s_mov_b32 m0, s42
	s_nop 0
	global_load_lds_dwordx4 v[162:163], off
	s_waitcnt vmcnt(8)
	s_waitcnt lgkmcnt(0)
	s_barrier
	v_mfma_f32_16x16x32_bf16 v[62:65], v[142:145], v[186:189], v[62:65]
	v_mfma_f32_16x16x32_bf16 v[58:61], v[158:161], v[186:189], v[58:61]
	v_mfma_f32_16x16x32_bf16 v[42:45], v[158:161], v[194:197], v[42:45]
	v_mfma_f32_16x16x32_bf16 v[46:49], v[142:145], v[194:197], v[46:49]
	v_mfma_f32_16x16x32_bf16 v[30:33], v[142:145], v[202:205], v[30:33]
	v_mfma_f32_16x16x32_bf16 v[26:29], v[158:161], v[202:205], v[26:29]
	v_mfma_f32_16x16x32_bf16 v[10:13], v[158:161], v[210:213], v[10:13]
	v_mfma_f32_16x16x32_bf16 v[14:17], v[142:145], v[210:213], v[14:17]
	v_mfma_f32_16x16x32_bf16 v[6:9], v[170:173], v[210:213], v[6:9]
	v_mfma_f32_16x16x32_bf16 v[2:5], v[178:181], v[210:213], v[2:5]
	v_mfma_f32_16x16x32_bf16 v[18:21], v[178:181], v[202:205], v[18:21]
	v_mfma_f32_16x16x32_bf16 v[22:25], v[170:173], v[202:205], v[22:25]
	v_mfma_f32_16x16x32_bf16 v[38:41], v[170:173], v[194:197], v[38:41]
	v_mfma_f32_16x16x32_bf16 v[34:37], v[178:181], v[194:197], v[34:37]
	v_mfma_f32_16x16x32_bf16 v[50:53], v[178:181], v[186:189], v[50:53]
	v_mfma_f32_16x16x32_bf16 v[54:57], v[170:173], v[186:189], v[54:57]
	v_mfma_f32_16x16x32_bf16 v[62:65], v[154:157], v[190:193], v[62:65]
	v_mfma_f32_16x16x32_bf16 v[58:61], v[166:169], v[190:193], v[58:61]
	v_mfma_f32_16x16x32_bf16 v[42:45], v[166:169], v[198:201], v[42:45]
	v_mfma_f32_16x16x32_bf16 v[46:49], v[154:157], v[198:201], v[46:49]
	v_mfma_f32_16x16x32_bf16 v[30:33], v[154:157], v[206:209], v[30:33]
	v_mfma_f32_16x16x32_bf16 v[26:29], v[166:169], v[206:209], v[26:29]
	v_mfma_f32_16x16x32_bf16 v[10:13], v[166:169], v[214:217], v[10:13]
	v_mfma_f32_16x16x32_bf16 v[14:17], v[154:157], v[214:217], v[14:17]
	v_mfma_f32_16x16x32_bf16 v[6:9], v[174:177], v[214:217], v[6:9]
	v_mfma_f32_16x16x32_bf16 v[2:5], v[182:185], v[214:217], v[2:5]
	v_mfma_f32_16x16x32_bf16 v[18:21], v[182:185], v[206:209], v[18:21]
	v_mfma_f32_16x16x32_bf16 v[22:25], v[174:177], v[206:209], v[22:25]
	v_mfma_f32_16x16x32_bf16 v[38:41], v[174:177], v[198:201], v[38:41]
	v_mfma_f32_16x16x32_bf16 v[34:37], v[182:185], v[198:201], v[34:37]
	v_mfma_f32_16x16x32_bf16 v[50:53], v[182:185], v[190:193], v[50:53]
	v_mfma_f32_16x16x32_bf16 v[54:57], v[174:177], v[190:193], v[54:57]
	s_barrier
	s_add_i32 s49, s49, 2
	s_add_u32 s26, s26, 0x100
	s_addc_u32 s27, s27, 0
	s_add_u32 s47, s47, 0x100
	s_addc_u32 s48, s48, 0
	s_cmp_gt_u32 s49, 29
	s_cbranch_scc0 .LBB0_1019
	s_setprio 0
	s_and_b64 vcc, exec, s[10:11]
	s_cbranch_vccz .LBB0_1022
	s_barrier

.Lsp_p9:
.LBB0_1220:
	ds_read_b128 v[142:145], v149
	ds_read_b128 v[154:157], v149 offset:1024
	ds_read_b128 v[158:161], v149 offset:2048
	ds_read_b128 v[166:169], v149 offset:3072
	ds_read_b128 v[170:173], v150
	ds_read_b128 v[174:177], v150 offset:1024
	ds_read_b128 v[178:181], v150 offset:2048
	ds_read_b128 v[182:185], v150 offset:3072
	s_add_u32 s30, s28, 0xfffe0080
	s_addc_u32 s31, s29, -1
	s_cmp_eq_u32 s51, 4
	s_cselect_b32 s35, s1, s31
	s_cselect_b32 s34, s17, s30
	s_cselect_b32 s31, s19, s50
	s_cselect_b32 s30, s48, s49
	v_lshl_add_u64 v[162:163], s[28:29], 0, v[138:139]
	s_add_i32 m0, s27, 0xc000
	ds_read_b128 v[186:189], v151
	ds_read_b128 v[190:193], v151 offset:1024
	ds_read_b128 v[194:197], v151 offset:2048
	ds_read_b128 v[198:201], v151 offset:3072
	ds_read_b128 v[202:205], v151 offset:4096
	ds_read_b128 v[206:209], v151 offset:5120
	ds_read_b128 v[210:213], v151 offset:6144
	ds_read_b128 v[214:217], v151 offset:7168
	global_load_lds_dwordx4 v[162:163], off
	v_lshl_add_u64 v[162:163], s[28:29], 0, v[140:141]
	s_add_i32 m0, s27, 0xe000
	s_nop 0
	global_load_lds_dwordx4 v[162:163], off
	s_waitcnt vmcnt(8)
	s_waitcnt lgkmcnt(0)
	s_barrier
	v_mfma_f32_16x16x32_bf16 v[126:129], v[142:145], v[186:189], v[126:129]
	v_mfma_f32_16x16x32_bf16 v[122:125], v[158:161], v[186:189], v[122:125]
	v_mfma_f32_16x16x32_bf16 v[106:109], v[158:161], v[194:197], v[106:109]
	v_mfma_f32_16x16x32_bf16 v[110:113], v[142:145], v[194:197], v[110:113]
	v_mfma_f32_16x16x32_bf16 v[94:97], v[142:145], v[202:205], v[94:97]
	v_mfma_f32_16x16x32_bf16 v[90:93], v[158:161], v[202:205], v[90:93]
	v_mfma_f32_16x16x32_bf16 v[74:77], v[158:161], v[210:213], v[74:77]
	v_mfma_f32_16x16x32_bf16 v[78:81], v[142:145], v[210:213], v[78:81]
	v_mfma_f32_16x16x32_bf16 v[70:73], v[170:173], v[210:213], v[70:73]
	v_mfma_f32_16x16x32_bf16 v[66:69], v[178:181], v[210:213], v[66:69]
	v_mfma_f32_16x16x32_bf16 v[82:85], v[178:181], v[202:205], v[82:85]
	v_mfma_f32_16x16x32_bf16 v[86:89], v[170:173], v[202:205], v[86:89]
	v_mfma_f32_16x16x32_bf16 v[102:105], v[170:173], v[194:197], v[102:105]
	v_mfma_f32_16x16x32_bf16 v[98:101], v[178:181], v[194:197], v[98:101]
	v_mfma_f32_16x16x32_bf16 v[114:117], v[178:181], v[186:189], v[114:117]
	v_mfma_f32_16x16x32_bf16 v[118:121], v[170:173], v[186:189], v[118:121]
	v_mfma_f32_16x16x32_bf16 v[126:129], v[154:157], v[190:193], v[126:129]
	v_mfma_f32_16x16x32_bf16 v[122:125], v[166:169], v[190:193], v[122:125]
	v_mfma_f32_16x16x32_bf16 v[106:109], v[166:169], v[198:201], v[106:109]
	v_mfma_f32_16x16x32_bf16 v[110:113], v[154:157], v[198:201], v[110:113]
	v_mfma_f32_16x16x32_bf16 v[94:97], v[154:157], v[206:209], v[94:97]
	v_mfma_f32_16x16x32_bf16 v[90:93], v[166:169], v[206:209], v[90:93]
	v_mfma_f32_16x16x32_bf16 v[74:77], v[166:169], v[214:217], v[74:77]
	v_mfma_f32_16x16x32_bf16 v[78:81], v[154:157], v[214:217], v[78:81]
	v_mfma_f32_16x16x32_bf16 v[70:73], v[174:177], v[214:217], v[70:73]
	v_mfma_f32_16x16x32_bf16 v[66:69], v[182:185], v[214:217], v[66:69]
	v_mfma_f32_16x16x32_bf16 v[82:85], v[182:185], v[206:209], v[82:85]
	v_mfma_f32_16x16x32_bf16 v[86:89], v[174:177], v[206:209], v[86:89]
	v_mfma_f32_16x16x32_bf16 v[102:105], v[174:177], v[198:201], v[102:105]
	v_mfma_f32_16x16x32_bf16 v[98:101], v[182:185], v[198:201], v[98:101]
	v_mfma_f32_16x16x32_bf16 v[114:117], v[182:185], v[190:193], v[114:117]
	v_mfma_f32_16x16x32_bf16 v[118:121], v[174:177], v[190:193], v[118:121]
	s_barrier
	s_add_i32 s52, s46, s2
	v_lshl_add_u64 v[162:163], s[30:31], 0, v[132:133]
	s_mov_b32 m0, s52
	ds_read_b128 v[186:189], v151 offset:16384
	ds_read_b128 v[190:193], v151 offset:17408
	ds_read_b128 v[194:197], v151 offset:18432
	ds_read_b128 v[198:201], v151 offset:19456
	ds_read_b128 v[202:205], v151 offset:20480
	ds_read_b128 v[206:209], v151 offset:21504
	ds_read_b128 v[210:213], v151 offset:22528
	ds_read_b128 v[214:217], v151 offset:23552
	global_load_lds_dwordx4 v[162:163], off
	s_add_i32 m0, s52, 0x2000
	s_add_u32 s52, s30, 0x20000
	v_lshl_add_u64 v[218:219], s[30:31], 0, v[136:137]
	s_addc_u32 s53, s31, 0
	s_add_i32 s54, s47, s2
	global_load_lds_dwordx4 v[218:219], off
	v_lshl_add_u64 v[220:221], s[52:53], 0, v[132:133]
	s_mov_b32 m0, s54
	v_lshl_add_u64 v[222:223], s[34:35], 0, v[134:135]
	global_load_lds_dwordx4 v[220:221], off
	v_lshl_add_u64 v[220:221], s[52:53], 0, v[136:137]
	s_add_i32 m0, s54, 0x2000
	s_nop 0
	global_load_lds_dwordx4 v[220:221], off
	v_lshl_add_u64 v[220:221], s[34:35], 0, v[130:131]
	s_mov_b32 m0, s27
	s_nop 0
	global_load_lds_dwordx4 v[220:221], off
	s_mov_b32 m0, s37
	s_nop 0
	global_load_lds_dwordx4 v[222:223], off
	s_waitcnt vmcnt(8)
	s_waitcnt lgkmcnt(0)
	s_barrier
	v_mfma_f32_16x16x32_bf16 v[62:65], v[142:145], v[186:189], v[62:65]
	v_mfma_f32_16x16x32_bf16 v[58:61], v[158:161], v[186:189], v[58:61]
	v_mfma_f32_16x16x32_bf16 v[42:45], v[158:161], v[194:197], v[42:45]
	v_mfma_f32_16x16x32_bf16 v[46:49], v[142:145], v[194:197], v[46:49]
	v_mfma_f32_16x16x32_bf16 v[30:33], v[142:145], v[202:205], v[30:33]
	v_mfma_f32_16x16x32_bf16 v[26:29], v[158:161], v[202:205], v[26:29]
	v_mfma_f32_16x16x32_bf16 v[10:13], v[158:161], v[210:213], v[10:13]
	v_mfma_f32_16x16x32_bf16 v[14:17], v[142:145], v[210:213], v[14:17]
	v_mfma_f32_16x16x32_bf16 v[6:9], v[170:173], v[210:213], v[6:9]
	v_mfma_f32_16x16x32_bf16 v[2:5], v[178:181], v[210:213], v[2:5]
	v_mfma_f32_16x16x32_bf16 v[18:21], v[178:181], v[202:205], v[18:21]
	v_mfma_f32_16x16x32_bf16 v[22:25], v[170:173], v[202:205], v[22:25]
	v_mfma_f32_16x16x32_bf16 v[38:41], v[170:173], v[194:197], v[38:41]
	v_mfma_f32_16x16x32_bf16 v[34:37], v[178:181], v[194:197], v[34:37]
	v_mfma_f32_16x16x32_bf16 v[50:53], v[178:181], v[186:189], v[50:53]
	v_mfma_f32_16x16x32_bf16 v[54:57], v[170:173], v[186:189], v[54:57]
	v_mfma_f32_16x16x32_bf16 v[62:65], v[154:157], v[190:193], v[62:65]
	v_mfma_f32_16x16x32_bf16 v[58:61], v[166:169], v[190:193], v[58:61]
	v_mfma_f32_16x16x32_bf16 v[42:45], v[166:169], v[198:201], v[42:45]
	v_mfma_f32_16x16x32_bf16 v[46:49], v[154:157], v[198:201], v[46:49]
	v_mfma_f32_16x16x32_bf16 v[30:33], v[154:157], v[206:209], v[30:33]
	v_mfma_f32_16x16x32_bf16 v[26:29], v[166:169], v[206:209], v[26:29]
	v_mfma_f32_16x16x32_bf16 v[10:13], v[166:169], v[214:217], v[10:13]
	v_mfma_f32_16x16x32_bf16 v[14:17], v[154:157], v[214:217], v[14:17]
	v_mfma_f32_16x16x32_bf16 v[6:9], v[174:177], v[214:217], v[6:9]
	v_mfma_f32_16x16x32_bf16 v[2:5], v[182:185], v[214:217], v[2:5]
	v_mfma_f32_16x16x32_bf16 v[18:21], v[182:185], v[206:209], v[18:21]
	v_mfma_f32_16x16x32_bf16 v[22:25], v[174:177], v[206:209], v[22:25]
	v_mfma_f32_16x16x32_bf16 v[38:41], v[174:177], v[198:201], v[38:41]
	v_mfma_f32_16x16x32_bf16 v[34:37], v[182:185], v[198:201], v[34:37]
	v_mfma_f32_16x16x32_bf16 v[50:53], v[182:185], v[190:193], v[50:53]
	v_mfma_f32_16x16x32_bf16 v[54:57], v[174:177], v[190:193], v[54:57]
	s_barrier
	s_add_i32 s52, 0, 0x18000
	v_add_u32_e32 v153, s52, v148
	s_add_i32 s53, 0, 0x1c000
	ds_read_b128 v[142:145], v153
	ds_read_b128 v[154:157], v153 offset:1024
	ds_read_b128 v[158:161], v153 offset:2048
	ds_read_b128 v[166:169], v153 offset:3072
	v_add_u32_e32 v153, s53, v148
	ds_read_b128 v[170:173], v153
	ds_read_b128 v[174:177], v153 offset:1024
	ds_read_b128 v[178:181], v153 offset:2048
	ds_read_b128 v[182:185], v153 offset:3072
	s_add_u32 s34, s34, 0x20000
	s_addc_u32 s35, s35, 0
	s_mov_b32 m0, s38
	v_lshl_add_u64 v[224:225], s[34:35], 0, v[130:131]
	ds_read_b128 v[186:189], v151 offset:32768
	ds_read_b128 v[190:193], v151 offset:33792
	ds_read_b128 v[194:197], v151 offset:34816
	ds_read_b128 v[198:201], v151 offset:35840
	ds_read_b128 v[202:205], v151 offset:36864
	ds_read_b128 v[206:209], v151 offset:37888
	ds_read_b128 v[210:213], v151 offset:38912
	ds_read_b128 v[214:217], v151 offset:39936
	global_load_lds_dwordx4 v[224:225], off
	v_lshl_add_u64 v[224:225], s[34:35], 0, v[134:135]
	s_mov_b32 m0, s39
	s_nop 0
	global_load_lds_dwordx4 v[224:225], off
	s_waitcnt vmcnt(8)
	s_waitcnt lgkmcnt(0)
	s_barrier
	v_mfma_f32_16x16x32_bf16 v[126:129], v[142:145], v[186:189], v[126:129]
	v_mfma_f32_16x16x32_bf16 v[122:125], v[158:161], v[186:189], v[122:125]
	v_mfma_f32_16x16x32_bf16 v[106:109], v[158:161], v[194:197], v[106:109]
	v_mfma_f32_16x16x32_bf16 v[110:113], v[142:145], v[194:197], v[110:113]
	v_mfma_f32_16x16x32_bf16 v[94:97], v[142:145], v[202:205], v[94:97]
	v_mfma_f32_16x16x32_bf16 v[90:93], v[158:161], v[202:205], v[90:93]
	v_mfma_f32_16x16x32_bf16 v[74:77], v[158:161], v[210:213], v[74:77]
	v_mfma_f32_16x16x32_bf16 v[78:81], v[142:145], v[210:213], v[78:81]
	v_mfma_f32_16x16x32_bf16 v[70:73], v[170:173], v[210:213], v[70:73]
	v_mfma_f32_16x16x32_bf16 v[66:69], v[178:181], v[210:213], v[66:69]
	v_mfma_f32_16x16x32_bf16 v[82:85], v[178:181], v[202:205], v[82:85]
	v_mfma_f32_16x16x32_bf16 v[86:89], v[170:173], v[202:205], v[86:89]
	v_mfma_f32_16x16x32_bf16 v[102:105], v[170:173], v[194:197], v[102:105]
	v_mfma_f32_16x16x32_bf16 v[98:101], v[178:181], v[194:197], v[98:101]
	v_mfma_f32_16x16x32_bf16 v[114:117], v[178:181], v[186:189], v[114:117]
	v_mfma_f32_16x16x32_bf16 v[118:121], v[170:173], v[186:189], v[118:121]
	v_mfma_f32_16x16x32_bf16 v[126:129], v[154:157], v[190:193], v[126:129]
	v_mfma_f32_16x16x32_bf16 v[122:125], v[166:169], v[190:193], v[122:125]
	v_mfma_f32_16x16x32_bf16 v[106:109], v[166:169], v[198:201], v[106:109]
	v_mfma_f32_16x16x32_bf16 v[110:113], v[154:157], v[198:201], v[110:113]
	v_mfma_f32_16x16x32_bf16 v[94:97], v[154:157], v[206:209], v[94:97]
	v_mfma_f32_16x16x32_bf16 v[90:93], v[166:169], v[206:209], v[90:93]
	v_mfma_f32_16x16x32_bf16 v[74:77], v[166:169], v[214:217], v[74:77]
	v_mfma_f32_16x16x32_bf16 v[78:81], v[154:157], v[214:217], v[78:81]
	v_mfma_f32_16x16x32_bf16 v[70:73], v[174:177], v[214:217], v[70:73]
	v_mfma_f32_16x16x32_bf16 v[66:69], v[182:185], v[214:217], v[66:69]
	v_mfma_f32_16x16x32_bf16 v[82:85], v[182:185], v[206:209], v[82:85]
	v_mfma_f32_16x16x32_bf16 v[86:89], v[174:177], v[206:209], v[86:89]
	v_mfma_f32_16x16x32_bf16 v[102:105], v[174:177], v[198:201], v[102:105]
	v_mfma_f32_16x16x32_bf16 v[98:101], v[182:185], v[198:201], v[98:101]
	v_mfma_f32_16x16x32_bf16 v[114:117], v[182:185], v[190:193], v[114:117]
	v_mfma_f32_16x16x32_bf16 v[118:121], v[174:177], v[190:193], v[118:121]
	s_barrier
	s_add_i32 s34, s52, s2
	v_lshl_add_u64 v[162:163], v[162:163], 0, s[10:11]
	s_mov_b32 m0, s34
	ds_read_b128 v[186:189], v151 offset:49152
	ds_read_b128 v[190:193], v151 offset:50176
	ds_read_b128 v[194:197], v151 offset:51200
	ds_read_b128 v[198:201], v151 offset:52224
	ds_read_b128 v[202:205], v151 offset:53248
	ds_read_b128 v[206:209], v151 offset:54272
	ds_read_b128 v[210:213], v151 offset:55296
	ds_read_b128 v[214:217], v151 offset:56320
	global_load_lds_dwordx4 v[162:163], off
	s_add_i32 m0, s34, 0x2000
	s_add_u32 s30, s30, 0x20080
	v_lshl_add_u64 v[162:163], v[218:219], 0, s[10:11]
	s_addc_u32 s31, s31, 0
	s_add_i32 s34, s53, s2
	global_load_lds_dwordx4 v[162:163], off
	v_lshl_add_u64 v[162:163], s[30:31], 0, v[132:133]
	s_mov_b32 m0, s34
	s_nop 0
	global_load_lds_dwordx4 v[162:163], off
	v_lshl_add_u64 v[162:163], s[30:31], 0, v[136:137]
	s_add_i32 m0, s34, 0x2000
	s_nop 0
	global_load_lds_dwordx4 v[162:163], off
	v_lshl_add_u64 v[162:163], v[220:221], 0, s[10:11]
	s_mov_b32 m0, s43
	s_nop 0
	global_load_lds_dwordx4 v[162:163], off
	v_lshl_add_u64 v[162:163], v[222:223], 0, s[10:11]
	s_mov_b32 m0, s44
	s_nop 0
	global_load_lds_dwordx4 v[162:163], off
	s_waitcnt vmcnt(8)
	s_waitcnt lgkmcnt(0)
	s_barrier
	v_mfma_f32_16x16x32_bf16 v[62:65], v[142:145], v[186:189], v[62:65]
	v_mfma_f32_16x16x32_bf16 v[58:61], v[158:161], v[186:189], v[58:61]
	v_mfma_f32_16x16x32_bf16 v[42:45], v[158:161], v[194:197], v[42:45]
	v_mfma_f32_16x16x32_bf16 v[46:49], v[142:145], v[194:197], v[46:49]
	v_mfma_f32_16x16x32_bf16 v[30:33], v[142:145], v[202:205], v[30:33]
	v_mfma_f32_16x16x32_bf16 v[26:29], v[158:161], v[202:205], v[26:29]
	v_mfma_f32_16x16x32_bf16 v[10:13], v[158:161], v[210:213], v[10:13]
	v_mfma_f32_16x16x32_bf16 v[14:17], v[142:145], v[210:213], v[14:17]
	v_mfma_f32_16x16x32_bf16 v[6:9], v[170:173], v[210:213], v[6:9]
	v_mfma_f32_16x16x32_bf16 v[2:5], v[178:181], v[210:213], v[2:5]
	v_mfma_f32_16x16x32_bf16 v[18:21], v[178:181], v[202:205], v[18:21]
	v_mfma_f32_16x16x32_bf16 v[22:25], v[170:173], v[202:205], v[22:25]
	v_mfma_f32_16x16x32_bf16 v[38:41], v[170:173], v[194:197], v[38:41]
	v_mfma_f32_16x16x32_bf16 v[34:37], v[178:181], v[194:197], v[34:37]
	v_mfma_f32_16x16x32_bf16 v[50:53], v[178:181], v[186:189], v[50:53]
	v_mfma_f32_16x16x32_bf16 v[54:57], v[170:173], v[186:189], v[54:57]
	v_mfma_f32_16x16x32_bf16 v[62:65], v[154:157], v[190:193], v[62:65]
	v_mfma_f32_16x16x32_bf16 v[58:61], v[166:169], v[190:193], v[58:61]
	v_mfma_f32_16x16x32_bf16 v[42:45], v[166:169], v[198:201], v[42:45]
	v_mfma_f32_16x16x32_bf16 v[46:49], v[154:157], v[198:201], v[46:49]
	v_mfma_f32_16x16x32_bf16 v[30:33], v[154:157], v[206:209], v[30:33]
	v_mfma_f32_16x16x32_bf16 v[26:29], v[166:169], v[206:209], v[26:29]
	v_mfma_f32_16x16x32_bf16 v[10:13], v[166:169], v[214:217], v[10:13]
	v_mfma_f32_16x16x32_bf16 v[14:17], v[154:157], v[214:217], v[14:17]
	v_mfma_f32_16x16x32_bf16 v[6:9], v[174:177], v[214:217], v[6:9]
	v_mfma_f32_16x16x32_bf16 v[2:5], v[182:185], v[214:217], v[2:5]
	v_mfma_f32_16x16x32_bf16 v[18:21], v[182:185], v[206:209], v[18:21]
	v_mfma_f32_16x16x32_bf16 v[22:25], v[174:177], v[206:209], v[22:25]
	v_mfma_f32_16x16x32_bf16 v[38:41], v[174:177], v[198:201], v[38:41]
	v_mfma_f32_16x16x32_bf16 v[34:37], v[182:185], v[198:201], v[34:37]
	v_mfma_f32_16x16x32_bf16 v[50:53], v[182:185], v[190:193], v[50:53]
	v_mfma_f32_16x16x32_bf16 v[54:57], v[174:177], v[190:193], v[54:57]
	s_barrier
	s_add_i32 s51, s51, 2
	s_add_u32 s28, s28, 0x100
	s_addc_u32 s29, s29, 0
	s_add_u32 s49, s49, 0x100
	s_addc_u32 s50, s50, 0
	s_cmp_gt_u32 s51, 5
	s_cbranch_scc0 .LBB0_1220
	s_setprio 0
	s_lshl_b32 s98, s26, 8
	s_add_i32 s98, s98, s41
	v_add_u32_e32 v240, s98, v146
	s_lshl_b32 s98, s0, 8
	s_or_b32 s98, s98, s42
	v_lshl_add_u32 v241, v147, 3, s98
	v_lshlrev_b32_e32 v240, 12, v240
	v_lshl_add_u32 v240, v241, 1, v240
	global_load_dwordx4 v[168:171], v240, s[62:63]
	global_load_dwordx4 v[172:175], v240, s[62:63] offset:256
	v_add_u32_e32 v240, 0x10000, v240
	global_load_dwordx4 v[176:179], v240, s[62:63]
	global_load_dwordx4 v[180:183], v240, s[62:63] offset:256
	v_add_u32_e32 v240, 0x10000, v240
	global_load_dwordx4 v[184:187], v240, s[62:63]
	global_load_dwordx4 v[188:191], v240, s[62:63] offset:256
	v_add_u32_e32 v240, 0x10000, v240
	global_load_dwordx4 v[192:195], v240, s[62:63]
	global_load_dwordx4 v[196:199], v240, s[62:63] offset:256
	v_add_u32_e32 v240, 0x50000, v240
	global_load_dwordx4 v[200:203], v240, s[62:63]
	global_load_dwordx4 v[204:207], v240, s[62:63] offset:256
	v_add_u32_e32 v240, 0x10000, v240
	global_load_dwordx4 v[208:211], v240, s[62:63]
	global_load_dwordx4 v[212:215], v240, s[62:63] offset:256
	v_add_u32_e32 v240, 0x10000, v240
	global_load_dwordx4 v[216:219], v240, s[62:63]
	global_load_dwordx4 v[220:223], v240, s[62:63] offset:256
	v_add_u32_e32 v240, 0x10000, v240
	global_load_dwordx4 v[224:227], v240, s[62:63]
	global_load_dwordx4 v[232:235], v240, s[62:63] offset:256
	s_and_b64 vcc, exec, s[12:13]
	s_cbranch_vccz .LBB0_1223
	s_barrier

.Lsp_p10:
.LBB0_1337:
	ds_read_b128 v[142:145], v149
	ds_read_b128 v[154:157], v149 offset:1024
	ds_read_b128 v[158:161], v149 offset:2048
	ds_read_b128 v[166:169], v149 offset:3072
	ds_read_b128 v[170:173], v150
	ds_read_b128 v[174:177], v150 offset:1024
	ds_read_b128 v[178:181], v150 offset:2048
	ds_read_b128 v[182:185], v150 offset:3072
	s_add_u32 s30, s28, 0xfff80080
	s_addc_u32 s31, s29, -1
	s_cmp_eq_u32 s54, 28
	s_cselect_b32 s35, s17, s31
	s_cselect_b32 s34, s19, s30
	s_cselect_b32 s31, s50, s53
	s_cselect_b32 s30, s51, s52
	v_lshl_add_u64 v[162:163], s[28:29], 0, v[138:139]
	s_add_i32 m0, s25, 0xc000
	ds_read_b128 v[186:189], v151
	ds_read_b128 v[190:193], v151 offset:1024
	ds_read_b128 v[194:197], v151 offset:2048
	ds_read_b128 v[198:201], v151 offset:3072
	ds_read_b128 v[202:205], v151 offset:4096
	ds_read_b128 v[206:209], v151 offset:5120
	ds_read_b128 v[210:213], v151 offset:6144
	ds_read_b128 v[214:217], v151 offset:7168
	global_load_lds_dwordx4 v[162:163], off
	v_lshl_add_u64 v[162:163], s[28:29], 0, v[140:141]
	s_add_i32 m0, s25, 0xe000
	s_nop 0
	global_load_lds_dwordx4 v[162:163], off
	s_waitcnt vmcnt(8)
	s_waitcnt lgkmcnt(0)
	s_barrier
	v_mfma_f32_16x16x32_bf16 v[122:125], v[142:145], v[186:189], v[122:125]
	v_mfma_f32_16x16x32_bf16 v[114:117], v[158:161], v[186:189], v[114:117]
	v_mfma_f32_16x16x32_bf16 v[98:101], v[158:161], v[194:197], v[98:101]
	v_mfma_f32_16x16x32_bf16 v[106:109], v[142:145], v[194:197], v[106:109]
	v_mfma_f32_16x16x32_bf16 v[90:93], v[142:145], v[202:205], v[90:93]
	v_mfma_f32_16x16x32_bf16 v[82:85], v[158:161], v[202:205], v[82:85]
	v_mfma_f32_16x16x32_bf16 v[66:69], v[158:161], v[210:213], v[66:69]
	v_mfma_f32_16x16x32_bf16 v[74:77], v[142:145], v[210:213], v[74:77]
	v_mfma_f32_16x16x32_bf16 v[78:81], v[170:173], v[210:213], v[78:81]
	v_mfma_f32_16x16x32_bf16 v[70:73], v[178:181], v[210:213], v[70:73]
	v_mfma_f32_16x16x32_bf16 v[86:89], v[178:181], v[202:205], v[86:89]
	v_mfma_f32_16x16x32_bf16 v[94:97], v[170:173], v[202:205], v[94:97]
	v_mfma_f32_16x16x32_bf16 v[110:113], v[170:173], v[194:197], v[110:113]
	v_mfma_f32_16x16x32_bf16 v[102:105], v[178:181], v[194:197], v[102:105]
	v_mfma_f32_16x16x32_bf16 v[118:121], v[178:181], v[186:189], v[118:121]
	v_mfma_f32_16x16x32_bf16 v[126:129], v[170:173], v[186:189], v[126:129]
	v_mfma_f32_16x16x32_bf16 v[122:125], v[154:157], v[190:193], v[122:125]
	v_mfma_f32_16x16x32_bf16 v[114:117], v[166:169], v[190:193], v[114:117]
	v_mfma_f32_16x16x32_bf16 v[98:101], v[166:169], v[198:201], v[98:101]
	v_mfma_f32_16x16x32_bf16 v[106:109], v[154:157], v[198:201], v[106:109]
	v_mfma_f32_16x16x32_bf16 v[90:93], v[154:157], v[206:209], v[90:93]
	v_mfma_f32_16x16x32_bf16 v[82:85], v[166:169], v[206:209], v[82:85]
	v_mfma_f32_16x16x32_bf16 v[66:69], v[166:169], v[214:217], v[66:69]
	v_mfma_f32_16x16x32_bf16 v[74:77], v[154:157], v[214:217], v[74:77]
	v_mfma_f32_16x16x32_bf16 v[78:81], v[174:177], v[214:217], v[78:81]
	v_mfma_f32_16x16x32_bf16 v[70:73], v[182:185], v[214:217], v[70:73]
	v_mfma_f32_16x16x32_bf16 v[86:89], v[182:185], v[206:209], v[86:89]
	v_mfma_f32_16x16x32_bf16 v[94:97], v[174:177], v[206:209], v[94:97]
	v_mfma_f32_16x16x32_bf16 v[110:113], v[174:177], v[198:201], v[110:113]
	v_mfma_f32_16x16x32_bf16 v[102:105], v[182:185], v[198:201], v[102:105]
	v_mfma_f32_16x16x32_bf16 v[118:121], v[182:185], v[190:193], v[118:121]
	v_mfma_f32_16x16x32_bf16 v[126:129], v[174:177], v[190:193], v[126:129]
	s_barrier
	s_add_i32 s55, s46, s36
	v_lshl_add_u64 v[162:163], s[30:31], 0, v[132:133]
	s_mov_b32 m0, s55
	ds_read_b128 v[186:189], v151 offset:16384
	ds_read_b128 v[190:193], v151 offset:17408
	ds_read_b128 v[194:197], v151 offset:18432
	ds_read_b128 v[198:201], v151 offset:19456
	ds_read_b128 v[202:205], v151 offset:20480
	ds_read_b128 v[206:209], v151 offset:21504
	ds_read_b128 v[210:213], v151 offset:22528
	ds_read_b128 v[214:217], v151 offset:23552
	global_load_lds_dwordx4 v[162:163], off
	s_add_i32 m0, s55, 0x2000
	s_add_u32 s56, s30, 0x80000
	v_lshl_add_u64 v[218:219], s[30:31], 0, v[136:137]
	s_addc_u32 s57, s31, 0
	s_add_i32 s55, s47, s36
	global_load_lds_dwordx4 v[218:219], off
	v_lshl_add_u64 v[220:221], s[56:57], 0, v[132:133]
	s_mov_b32 m0, s55
	v_lshl_add_u64 v[222:223], s[34:35], 0, v[134:135]
	global_load_lds_dwordx4 v[220:221], off
	v_lshl_add_u64 v[220:221], s[56:57], 0, v[136:137]
	s_add_i32 m0, s55, 0x2000
	s_nop 0
	global_load_lds_dwordx4 v[220:221], off
	v_lshl_add_u64 v[220:221], s[34:35], 0, v[130:131]
	s_mov_b32 m0, s25
	s_nop 0
	global_load_lds_dwordx4 v[220:221], off
	s_mov_b32 m0, s27
	s_nop 0
	global_load_lds_dwordx4 v[222:223], off
	s_waitcnt vmcnt(8)
	s_waitcnt lgkmcnt(0)
	s_barrier
	v_mfma_f32_16x16x32_bf16 v[58:61], v[142:145], v[186:189], v[58:61]
	v_mfma_f32_16x16x32_bf16 v[50:53], v[158:161], v[186:189], v[50:53]
	v_mfma_f32_16x16x32_bf16 v[34:37], v[158:161], v[194:197], v[34:37]
	v_mfma_f32_16x16x32_bf16 v[42:45], v[142:145], v[194:197], v[42:45]
	v_mfma_f32_16x16x32_bf16 v[26:29], v[142:145], v[202:205], v[26:29]
	v_mfma_f32_16x16x32_bf16 v[18:21], v[158:161], v[202:205], v[18:21]
	v_mfma_f32_16x16x32_bf16 v[2:5], v[158:161], v[210:213], v[2:5]
	v_mfma_f32_16x16x32_bf16 v[10:13], v[142:145], v[210:213], v[10:13]
	v_mfma_f32_16x16x32_bf16 v[14:17], v[170:173], v[210:213], v[14:17]
	v_mfma_f32_16x16x32_bf16 v[6:9], v[178:181], v[210:213], v[6:9]
	v_mfma_f32_16x16x32_bf16 v[22:25], v[178:181], v[202:205], v[22:25]
	v_mfma_f32_16x16x32_bf16 v[30:33], v[170:173], v[202:205], v[30:33]
	v_mfma_f32_16x16x32_bf16 v[46:49], v[170:173], v[194:197], v[46:49]
	v_mfma_f32_16x16x32_bf16 v[38:41], v[178:181], v[194:197], v[38:41]
	v_mfma_f32_16x16x32_bf16 v[54:57], v[178:181], v[186:189], v[54:57]
	v_mfma_f32_16x16x32_bf16 v[62:65], v[170:173], v[186:189], v[62:65]
	v_mfma_f32_16x16x32_bf16 v[58:61], v[154:157], v[190:193], v[58:61]
	v_mfma_f32_16x16x32_bf16 v[50:53], v[166:169], v[190:193], v[50:53]
	v_mfma_f32_16x16x32_bf16 v[34:37], v[166:169], v[198:201], v[34:37]
	v_mfma_f32_16x16x32_bf16 v[42:45], v[154:157], v[198:201], v[42:45]
	v_mfma_f32_16x16x32_bf16 v[26:29], v[154:157], v[206:209], v[26:29]
	v_mfma_f32_16x16x32_bf16 v[18:21], v[166:169], v[206:209], v[18:21]
	v_mfma_f32_16x16x32_bf16 v[2:5], v[166:169], v[214:217], v[2:5]
	v_mfma_f32_16x16x32_bf16 v[10:13], v[154:157], v[214:217], v[10:13]
	v_mfma_f32_16x16x32_bf16 v[14:17], v[174:177], v[214:217], v[14:17]
	v_mfma_f32_16x16x32_bf16 v[6:9], v[182:185], v[214:217], v[6:9]
	v_mfma_f32_16x16x32_bf16 v[22:25], v[182:185], v[206:209], v[22:25]
	v_mfma_f32_16x16x32_bf16 v[30:33], v[174:177], v[206:209], v[30:33]
	v_mfma_f32_16x16x32_bf16 v[46:49], v[174:177], v[198:201], v[46:49]
	v_mfma_f32_16x16x32_bf16 v[38:41], v[182:185], v[198:201], v[38:41]
	v_mfma_f32_16x16x32_bf16 v[54:57], v[182:185], v[190:193], v[54:57]
	v_mfma_f32_16x16x32_bf16 v[62:65], v[174:177], v[190:193], v[62:65]
	s_barrier
	s_add_i32 s55, 0, 0x18000
	v_add_u32_e32 v153, s55, v148
	s_add_i32 s56, 0, 0x1c000
	ds_read_b128 v[142:145], v153
	ds_read_b128 v[154:157], v153 offset:1024
	ds_read_b128 v[158:161], v153 offset:2048
	ds_read_b128 v[166:169], v153 offset:3072
	v_add_u32_e32 v153, s56, v148
	ds_read_b128 v[170:173], v153
	ds_read_b128 v[174:177], v153 offset:1024
	ds_read_b128 v[178:181], v153 offset:2048
	ds_read_b128 v[182:185], v153 offset:3072
	s_add_u32 s34, s34, 0x80000
	s_addc_u32 s35, s35, 0
	s_mov_b32 m0, s37
	v_lshl_add_u64 v[224:225], s[34:35], 0, v[130:131]
	ds_read_b128 v[186:189], v151 offset:32768
	ds_read_b128 v[190:193], v151 offset:33792
	ds_read_b128 v[194:197], v151 offset:34816
	ds_read_b128 v[198:201], v151 offset:35840
	ds_read_b128 v[202:205], v151 offset:36864
	ds_read_b128 v[206:209], v151 offset:37888
	ds_read_b128 v[210:213], v151 offset:38912
	ds_read_b128 v[214:217], v151 offset:39936
	global_load_lds_dwordx4 v[224:225], off
	v_lshl_add_u64 v[224:225], s[34:35], 0, v[134:135]
	s_mov_b32 m0, s38
	s_nop 0
	global_load_lds_dwordx4 v[224:225], off
	s_waitcnt vmcnt(8)
	s_waitcnt lgkmcnt(0)
	s_barrier
	v_mfma_f32_16x16x32_bf16 v[122:125], v[142:145], v[186:189], v[122:125]
	v_mfma_f32_16x16x32_bf16 v[114:117], v[158:161], v[186:189], v[114:117]
	v_mfma_f32_16x16x32_bf16 v[98:101], v[158:161], v[194:197], v[98:101]
	v_mfma_f32_16x16x32_bf16 v[106:109], v[142:145], v[194:197], v[106:109]
	v_mfma_f32_16x16x32_bf16 v[90:93], v[142:145], v[202:205], v[90:93]
	v_mfma_f32_16x16x32_bf16 v[82:85], v[158:161], v[202:205], v[82:85]
	v_mfma_f32_16x16x32_bf16 v[66:69], v[158:161], v[210:213], v[66:69]
	v_mfma_f32_16x16x32_bf16 v[74:77], v[142:145], v[210:213], v[74:77]
	v_mfma_f32_16x16x32_bf16 v[78:81], v[170:173], v[210:213], v[78:81]
	v_mfma_f32_16x16x32_bf16 v[70:73], v[178:181], v[210:213], v[70:73]
	v_mfma_f32_16x16x32_bf16 v[86:89], v[178:181], v[202:205], v[86:89]
	v_mfma_f32_16x16x32_bf16 v[94:97], v[170:173], v[202:205], v[94:97]
	v_mfma_f32_16x16x32_bf16 v[110:113], v[170:173], v[194:197], v[110:113]
	v_mfma_f32_16x16x32_bf16 v[102:105], v[178:181], v[194:197], v[102:105]
	v_mfma_f32_16x16x32_bf16 v[118:121], v[178:181], v[186:189], v[118:121]
	v_mfma_f32_16x16x32_bf16 v[126:129], v[170:173], v[186:189], v[126:129]
	v_mfma_f32_16x16x32_bf16 v[122:125], v[154:157], v[190:193], v[122:125]
	v_mfma_f32_16x16x32_bf16 v[114:117], v[166:169], v[190:193], v[114:117]
	v_mfma_f32_16x16x32_bf16 v[98:101], v[166:169], v[198:201], v[98:101]
	v_mfma_f32_16x16x32_bf16 v[106:109], v[154:157], v[198:201], v[106:109]
	v_mfma_f32_16x16x32_bf16 v[90:93], v[154:157], v[206:209], v[90:93]
	v_mfma_f32_16x16x32_bf16 v[82:85], v[166:169], v[206:209], v[82:85]
	v_mfma_f32_16x16x32_bf16 v[66:69], v[166:169], v[214:217], v[66:69]
	v_mfma_f32_16x16x32_bf16 v[74:77], v[154:157], v[214:217], v[74:77]
	v_mfma_f32_16x16x32_bf16 v[78:81], v[174:177], v[214:217], v[78:81]
	v_mfma_f32_16x16x32_bf16 v[70:73], v[182:185], v[214:217], v[70:73]
	v_mfma_f32_16x16x32_bf16 v[86:89], v[182:185], v[206:209], v[86:89]
	v_mfma_f32_16x16x32_bf16 v[94:97], v[174:177], v[206:209], v[94:97]
	v_mfma_f32_16x16x32_bf16 v[110:113], v[174:177], v[198:201], v[110:113]
	v_mfma_f32_16x16x32_bf16 v[102:105], v[182:185], v[198:201], v[102:105]
	v_mfma_f32_16x16x32_bf16 v[118:121], v[182:185], v[190:193], v[118:121]
	v_mfma_f32_16x16x32_bf16 v[126:129], v[174:177], v[190:193], v[126:129]
	s_barrier
	s_add_i32 s34, s55, s36
	v_lshl_add_u64 v[162:163], v[162:163], 0, s[12:13]
	s_mov_b32 m0, s34
	ds_read_b128 v[186:189], v151 offset:49152
	ds_read_b128 v[190:193], v151 offset:50176
	ds_read_b128 v[194:197], v151 offset:51200
	ds_read_b128 v[198:201], v151 offset:52224
	ds_read_b128 v[202:205], v151 offset:53248
	ds_read_b128 v[206:209], v151 offset:54272
	ds_read_b128 v[210:213], v151 offset:55296
	ds_read_b128 v[214:217], v151 offset:56320
	global_load_lds_dwordx4 v[162:163], off
	s_add_i32 m0, s34, 0x2000
	s_add_u32 s30, s30, 0x80080
	v_lshl_add_u64 v[162:163], v[218:219], 0, s[12:13]
	s_addc_u32 s31, s31, 0
	s_add_i32 s34, s56, s36
	global_load_lds_dwordx4 v[162:163], off
	v_lshl_add_u64 v[162:163], s[30:31], 0, v[132:133]
	s_mov_b32 m0, s34
	s_nop 0
	global_load_lds_dwordx4 v[162:163], off
	v_lshl_add_u64 v[162:163], s[30:31], 0, v[136:137]
	s_add_i32 m0, s34, 0x2000
	s_nop 0
	global_load_lds_dwordx4 v[162:163], off
	v_lshl_add_u64 v[162:163], v[220:221], 0, s[12:13]
	s_mov_b32 m0, s42
	s_nop 0
	global_load_lds_dwordx4 v[162:163], off
	v_lshl_add_u64 v[162:163], v[222:223], 0, s[12:13]
	s_mov_b32 m0, s43
	s_nop 0
	global_load_lds_dwordx4 v[162:163], off
	s_waitcnt vmcnt(8)
	s_waitcnt lgkmcnt(0)
	s_barrier
	v_mfma_f32_16x16x32_bf16 v[58:61], v[142:145], v[186:189], v[58:61]
	v_mfma_f32_16x16x32_bf16 v[50:53], v[158:161], v[186:189], v[50:53]
	v_mfma_f32_16x16x32_bf16 v[34:37], v[158:161], v[194:197], v[34:37]
	v_mfma_f32_16x16x32_bf16 v[42:45], v[142:145], v[194:197], v[42:45]
	v_mfma_f32_16x16x32_bf16 v[26:29], v[142:145], v[202:205], v[26:29]
	v_mfma_f32_16x16x32_bf16 v[18:21], v[158:161], v[202:205], v[18:21]
	v_mfma_f32_16x16x32_bf16 v[2:5], v[158:161], v[210:213], v[2:5]
	v_mfma_f32_16x16x32_bf16 v[10:13], v[142:145], v[210:213], v[10:13]
	v_mfma_f32_16x16x32_bf16 v[14:17], v[170:173], v[210:213], v[14:17]
	v_mfma_f32_16x16x32_bf16 v[6:9], v[178:181], v[210:213], v[6:9]
	v_mfma_f32_16x16x32_bf16 v[22:25], v[178:181], v[202:205], v[22:25]
	v_mfma_f32_16x16x32_bf16 v[30:33], v[170:173], v[202:205], v[30:33]
	v_mfma_f32_16x16x32_bf16 v[46:49], v[170:173], v[194:197], v[46:49]
	v_mfma_f32_16x16x32_bf16 v[38:41], v[178:181], v[194:197], v[38:41]
	v_mfma_f32_16x16x32_bf16 v[54:57], v[178:181], v[186:189], v[54:57]
	v_mfma_f32_16x16x32_bf16 v[62:65], v[170:173], v[186:189], v[62:65]
	v_mfma_f32_16x16x32_bf16 v[58:61], v[154:157], v[190:193], v[58:61]
	v_mfma_f32_16x16x32_bf16 v[50:53], v[166:169], v[190:193], v[50:53]
	v_mfma_f32_16x16x32_bf16 v[34:37], v[166:169], v[198:201], v[34:37]
	v_mfma_f32_16x16x32_bf16 v[42:45], v[154:157], v[198:201], v[42:45]
	v_mfma_f32_16x16x32_bf16 v[26:29], v[154:157], v[206:209], v[26:29]
	v_mfma_f32_16x16x32_bf16 v[18:21], v[166:169], v[206:209], v[18:21]
	v_mfma_f32_16x16x32_bf16 v[2:5], v[166:169], v[214:217], v[2:5]
	v_mfma_f32_16x16x32_bf16 v[10:13], v[154:157], v[214:217], v[10:13]
	v_mfma_f32_16x16x32_bf16 v[14:17], v[174:177], v[214:217], v[14:17]
	v_mfma_f32_16x16x32_bf16 v[6:9], v[182:185], v[214:217], v[6:9]
	v_mfma_f32_16x16x32_bf16 v[22:25], v[182:185], v[206:209], v[22:25]
	v_mfma_f32_16x16x32_bf16 v[30:33], v[174:177], v[206:209], v[30:33]
	v_mfma_f32_16x16x32_bf16 v[46:49], v[174:177], v[198:201], v[46:49]
	v_mfma_f32_16x16x32_bf16 v[38:41], v[182:185], v[198:201], v[38:41]
	v_mfma_f32_16x16x32_bf16 v[54:57], v[182:185], v[190:193], v[54:57]
	v_mfma_f32_16x16x32_bf16 v[62:65], v[174:177], v[190:193], v[62:65]
	s_barrier
	s_add_i32 s54, s54, 2
	s_add_u32 s28, s28, 0x100
	s_addc_u32 s29, s29, 0
	s_add_u32 s52, s52, 0x100
	s_addc_u32 s53, s53, 0
	s_cmp_gt_u32 s54, 29
	s_cbranch_scc0 .LBB0_1337
	s_setprio 0
	v_mov_b32_e32 v142, v1
	v_mov_b32_e32 v153, v147
	v_mov_b32_e32 v143, v165
	v_mov_b32_e32 v144, v146
	s_lshl_b32 s17, s26, 8
	s_add_i32 s17, s17, s40
	v_add_u32_e32 v142, s17, v144
	v_ashrrev_i32_e32 v143, 31, v142
	v_lshl_add_u64 v[144:145], v[142:143], 2, s[10:11]
	global_load_dword v229, v[144:145], off
	global_load_dword v230, v[144:145], off offset:64
	global_load_dword v231, v[144:145], off offset:128
	global_load_dword v232, v[144:145], off offset:192
	global_load_dword v233, v[144:145], off offset:512
	global_load_dword v234, v[144:145], off offset:576
	global_load_dword v235, v[144:145], off offset:640
	global_load_dword v236, v[144:145], off offset:704
	s_and_b64 vcc, exec, s[14:15]
	s_cbranch_vccz .LBB0_1340
	s_barrier

.Lsp_p11:
.LBB0_1449:
	ds_read_b128 v[140:143], v167
	ds_read_b128 v[144:147], v167 offset:1024
	ds_read_b128 v[148:151], v167 offset:2048
	ds_read_b128 v[152:155], v167 offset:3072
	ds_read_b128 v[156:159], v168
	ds_read_b128 v[172:175], v168 offset:1024
	ds_read_b128 v[176:179], v168 offset:2048
	ds_read_b128 v[180:183], v168 offset:3072
	s_add_u32 s20, s0, 0xffea0080
	s_addc_u32 s21, s1, -1
	s_cmpk_eq_i32 s52, 0x54
	s_cselect_b32 s23, s25, s21
	s_cselect_b32 s22, s47, s20
	s_cselect_b32 s21, s48, s51
	s_cselect_b32 s20, s49, s50
	v_lshl_add_u64 v[160:161], s[0:1], 0, v[136:137]
	s_add_i32 m0, s29, 0xc000
	ds_read_b128 v[184:187], v169
	ds_read_b128 v[188:191], v169 offset:1024
	ds_read_b128 v[192:195], v169 offset:2048
	ds_read_b128 v[196:199], v169 offset:3072
	ds_read_b128 v[200:203], v169 offset:4096
	ds_read_b128 v[204:207], v169 offset:5120
	ds_read_b128 v[208:211], v169 offset:6144
	ds_read_b128 v[212:215], v169 offset:7168
	global_load_lds_dwordx4 v[160:161], off
	v_lshl_add_u64 v[160:161], s[0:1], 0, v[138:139]
	s_add_i32 m0, s29, 0xe000
	s_nop 0
	global_load_lds_dwordx4 v[160:161], off
	s_waitcnt vmcnt(8)
	s_waitcnt lgkmcnt(0)
	s_barrier
	v_mfma_f32_16x16x32_bf16 v[124:127], v[140:143], v[184:187], v[124:127]
	v_mfma_f32_16x16x32_bf16 v[120:123], v[148:151], v[184:187], v[120:123]
	v_mfma_f32_16x16x32_bf16 v[104:107], v[148:151], v[192:195], v[104:107]
	v_mfma_f32_16x16x32_bf16 v[108:111], v[140:143], v[192:195], v[108:111]
	v_mfma_f32_16x16x32_bf16 v[92:95], v[140:143], v[200:203], v[92:95]
	v_mfma_f32_16x16x32_bf16 v[88:91], v[148:151], v[200:203], v[88:91]
	v_mfma_f32_16x16x32_bf16 v[72:75], v[148:151], v[208:211], v[72:75]
	v_mfma_f32_16x16x32_bf16 v[76:79], v[140:143], v[208:211], v[76:79]
	v_mfma_f32_16x16x32_bf16 v[68:71], v[156:159], v[208:211], v[68:71]
	v_mfma_f32_16x16x32_bf16 v[64:67], v[176:179], v[208:211], v[64:67]
	v_mfma_f32_16x16x32_bf16 v[80:83], v[176:179], v[200:203], v[80:83]
	v_mfma_f32_16x16x32_bf16 v[84:87], v[156:159], v[200:203], v[84:87]
	v_mfma_f32_16x16x32_bf16 v[100:103], v[156:159], v[192:195], v[100:103]
	v_mfma_f32_16x16x32_bf16 v[96:99], v[176:179], v[192:195], v[96:99]
	v_mfma_f32_16x16x32_bf16 v[112:115], v[176:179], v[184:187], v[112:115]
	v_mfma_f32_16x16x32_bf16 v[116:119], v[156:159], v[184:187], v[116:119]
	v_mfma_f32_16x16x32_bf16 v[124:127], v[144:147], v[188:191], v[124:127]
	v_mfma_f32_16x16x32_bf16 v[120:123], v[152:155], v[188:191], v[120:123]
	v_mfma_f32_16x16x32_bf16 v[104:107], v[152:155], v[196:199], v[104:107]
	v_mfma_f32_16x16x32_bf16 v[108:111], v[144:147], v[196:199], v[108:111]
	v_mfma_f32_16x16x32_bf16 v[92:95], v[144:147], v[204:207], v[92:95]
	v_mfma_f32_16x16x32_bf16 v[88:91], v[152:155], v[204:207], v[88:91]
	v_mfma_f32_16x16x32_bf16 v[72:75], v[152:155], v[212:215], v[72:75]
	v_mfma_f32_16x16x32_bf16 v[76:79], v[144:147], v[212:215], v[76:79]
	v_mfma_f32_16x16x32_bf16 v[68:71], v[172:175], v[212:215], v[68:71]
	v_mfma_f32_16x16x32_bf16 v[64:67], v[180:183], v[212:215], v[64:67]
	v_mfma_f32_16x16x32_bf16 v[80:83], v[180:183], v[204:207], v[80:83]
	v_mfma_f32_16x16x32_bf16 v[84:87], v[172:175], v[204:207], v[84:87]
	v_mfma_f32_16x16x32_bf16 v[100:103], v[172:175], v[196:199], v[100:103]
	v_mfma_f32_16x16x32_bf16 v[96:99], v[180:183], v[196:199], v[96:99]
	v_mfma_f32_16x16x32_bf16 v[112:115], v[180:183], v[188:191], v[112:115]
	v_mfma_f32_16x16x32_bf16 v[116:119], v[172:175], v[188:191], v[116:119]
	s_barrier
	s_add_i32 s53, s42, s28
	v_lshl_add_u64 v[160:161], s[20:21], 0, v[130:131]
	s_mov_b32 m0, s53
	ds_read_b128 v[184:187], v169 offset:16384
	ds_read_b128 v[188:191], v169 offset:17408
	ds_read_b128 v[192:195], v169 offset:18432
	ds_read_b128 v[196:199], v169 offset:19456
	ds_read_b128 v[200:203], v169 offset:20480
	ds_read_b128 v[204:207], v169 offset:21504
	ds_read_b128 v[208:211], v169 offset:22528
	ds_read_b128 v[212:215], v169 offset:23552
	global_load_lds_dwordx4 v[160:161], off
	s_add_i32 m0, s53, 0x2000
	s_add_u32 s54, s20, 0x160000
	v_lshl_add_u64 v[216:217], s[20:21], 0, v[134:135]
	s_addc_u32 s55, s21, 0
	s_add_i32 s53, s43, s28
	global_load_lds_dwordx4 v[216:217], off
	v_lshl_add_u64 v[218:219], s[54:55], 0, v[130:131]
	s_mov_b32 m0, s53
	v_lshl_add_u64 v[220:221], s[22:23], 0, v[132:133]
	global_load_lds_dwordx4 v[218:219], off
	v_lshl_add_u64 v[218:219], s[54:55], 0, v[134:135]
	s_add_i32 m0, s53, 0x2000
	s_nop 0
	global_load_lds_dwordx4 v[218:219], off
	v_lshl_add_u64 v[218:219], s[22:23], 0, v[128:129]
	s_mov_b32 m0, s29
	s_nop 0
	global_load_lds_dwordx4 v[218:219], off
	s_mov_b32 m0, s30
	s_nop 0
	global_load_lds_dwordx4 v[220:221], off
	s_waitcnt vmcnt(8)
	s_waitcnt lgkmcnt(0)
	s_barrier
	v_mfma_f32_16x16x32_bf16 v[60:63], v[140:143], v[184:187], v[60:63]
	v_mfma_f32_16x16x32_bf16 v[56:59], v[148:151], v[184:187], v[56:59]
	v_mfma_f32_16x16x32_bf16 v[40:43], v[148:151], v[192:195], v[40:43]
	v_mfma_f32_16x16x32_bf16 v[44:47], v[140:143], v[192:195], v[44:47]
	v_mfma_f32_16x16x32_bf16 v[28:31], v[140:143], v[200:203], v[28:31]
	v_mfma_f32_16x16x32_bf16 v[24:27], v[148:151], v[200:203], v[24:27]
	v_mfma_f32_16x16x32_bf16 v[8:11], v[148:151], v[208:211], v[8:11]
	v_mfma_f32_16x16x32_bf16 v[12:15], v[140:143], v[208:211], v[12:15]
	v_mfma_f32_16x16x32_bf16 v[4:7], v[156:159], v[208:211], v[4:7]
	v_mfma_f32_16x16x32_bf16 v[0:3], v[176:179], v[208:211], v[0:3]
	v_mfma_f32_16x16x32_bf16 v[16:19], v[176:179], v[200:203], v[16:19]
	v_mfma_f32_16x16x32_bf16 v[20:23], v[156:159], v[200:203], v[20:23]
	v_mfma_f32_16x16x32_bf16 v[36:39], v[156:159], v[192:195], v[36:39]
	v_mfma_f32_16x16x32_bf16 v[32:35], v[176:179], v[192:195], v[32:35]
	v_mfma_f32_16x16x32_bf16 v[48:51], v[176:179], v[184:187], v[48:51]
	v_mfma_f32_16x16x32_bf16 v[52:55], v[156:159], v[184:187], v[52:55]
	v_mfma_f32_16x16x32_bf16 v[60:63], v[144:147], v[188:191], v[60:63]
	v_mfma_f32_16x16x32_bf16 v[56:59], v[152:155], v[188:191], v[56:59]
	v_mfma_f32_16x16x32_bf16 v[40:43], v[152:155], v[196:199], v[40:43]
	v_mfma_f32_16x16x32_bf16 v[44:47], v[144:147], v[196:199], v[44:47]
	v_mfma_f32_16x16x32_bf16 v[28:31], v[144:147], v[204:207], v[28:31]
	v_mfma_f32_16x16x32_bf16 v[24:27], v[152:155], v[204:207], v[24:27]
	v_mfma_f32_16x16x32_bf16 v[8:11], v[152:155], v[212:215], v[8:11]
	v_mfma_f32_16x16x32_bf16 v[12:15], v[144:147], v[212:215], v[12:15]
	v_mfma_f32_16x16x32_bf16 v[4:7], v[172:175], v[212:215], v[4:7]
	v_mfma_f32_16x16x32_bf16 v[0:3], v[180:183], v[212:215], v[0:3]
	v_mfma_f32_16x16x32_bf16 v[16:19], v[180:183], v[204:207], v[16:19]
	v_mfma_f32_16x16x32_bf16 v[20:23], v[172:175], v[204:207], v[20:23]
	v_mfma_f32_16x16x32_bf16 v[36:39], v[172:175], v[196:199], v[36:39]
	v_mfma_f32_16x16x32_bf16 v[32:35], v[180:183], v[196:199], v[32:35]
	v_mfma_f32_16x16x32_bf16 v[48:51], v[180:183], v[188:191], v[48:51]
	v_mfma_f32_16x16x32_bf16 v[52:55], v[172:175], v[188:191], v[52:55]
	s_barrier
	s_add_i32 s53, 0, 0x18000
	s_add_i32 s54, 0, 0x1c000
	v_add_u32_e32 v152, s53, v166
	v_add_u32_e32 v180, s54, v166
	ds_read_b128 v[140:143], v152
	ds_read_b128 v[144:147], v152 offset:1024
	ds_read_b128 v[148:151], v152 offset:2048
	ds_read_b128 v[152:155], v152 offset:3072
	ds_read_b128 v[156:159], v180
	ds_read_b128 v[172:175], v180 offset:1024
	ds_read_b128 v[176:179], v180 offset:2048
	ds_read_b128 v[180:183], v180 offset:3072
	s_add_u32 s22, s22, 0x160000
	s_addc_u32 s23, s23, 0
	s_mov_b32 m0, s31
	v_lshl_add_u64 v[222:223], s[22:23], 0, v[128:129]
	ds_read_b128 v[184:187], v169 offset:32768
	ds_read_b128 v[188:191], v169 offset:33792
	ds_read_b128 v[192:195], v169 offset:34816
	ds_read_b128 v[196:199], v169 offset:35840
	ds_read_b128 v[200:203], v169 offset:36864
	ds_read_b128 v[204:207], v169 offset:37888
	ds_read_b128 v[208:211], v169 offset:38912
	ds_read_b128 v[212:215], v169 offset:39936
	global_load_lds_dwordx4 v[222:223], off
	v_lshl_add_u64 v[222:223], s[22:23], 0, v[132:133]
	s_mov_b32 m0, s33
	s_nop 0
	global_load_lds_dwordx4 v[222:223], off
	s_waitcnt vmcnt(8)
	s_waitcnt lgkmcnt(0)
	s_barrier
	v_mfma_f32_16x16x32_bf16 v[124:127], v[140:143], v[184:187], v[124:127]
	v_mfma_f32_16x16x32_bf16 v[120:123], v[148:151], v[184:187], v[120:123]
	v_mfma_f32_16x16x32_bf16 v[104:107], v[148:151], v[192:195], v[104:107]
	v_mfma_f32_16x16x32_bf16 v[108:111], v[140:143], v[192:195], v[108:111]
	v_mfma_f32_16x16x32_bf16 v[92:95], v[140:143], v[200:203], v[92:95]
	v_mfma_f32_16x16x32_bf16 v[88:91], v[148:151], v[200:203], v[88:91]
	v_mfma_f32_16x16x32_bf16 v[72:75], v[148:151], v[208:211], v[72:75]
	v_mfma_f32_16x16x32_bf16 v[76:79], v[140:143], v[208:211], v[76:79]
	v_mfma_f32_16x16x32_bf16 v[68:71], v[156:159], v[208:211], v[68:71]
	v_mfma_f32_16x16x32_bf16 v[64:67], v[176:179], v[208:211], v[64:67]
	v_mfma_f32_16x16x32_bf16 v[80:83], v[176:179], v[200:203], v[80:83]
	v_mfma_f32_16x16x32_bf16 v[84:87], v[156:159], v[200:203], v[84:87]
	v_mfma_f32_16x16x32_bf16 v[100:103], v[156:159], v[192:195], v[100:103]
	v_mfma_f32_16x16x32_bf16 v[96:99], v[176:179], v[192:195], v[96:99]
	v_mfma_f32_16x16x32_bf16 v[112:115], v[176:179], v[184:187], v[112:115]
	v_mfma_f32_16x16x32_bf16 v[116:119], v[156:159], v[184:187], v[116:119]
	v_mfma_f32_16x16x32_bf16 v[124:127], v[144:147], v[188:191], v[124:127]
	v_mfma_f32_16x16x32_bf16 v[120:123], v[152:155], v[188:191], v[120:123]
	v_mfma_f32_16x16x32_bf16 v[104:107], v[152:155], v[196:199], v[104:107]
	v_mfma_f32_16x16x32_bf16 v[108:111], v[144:147], v[196:199], v[108:111]
	v_mfma_f32_16x16x32_bf16 v[92:95], v[144:147], v[204:207], v[92:95]
	v_mfma_f32_16x16x32_bf16 v[88:91], v[152:155], v[204:207], v[88:91]
	v_mfma_f32_16x16x32_bf16 v[72:75], v[152:155], v[212:215], v[72:75]
	v_mfma_f32_16x16x32_bf16 v[76:79], v[144:147], v[212:215], v[76:79]
	v_mfma_f32_16x16x32_bf16 v[68:71], v[172:175], v[212:215], v[68:71]
	v_mfma_f32_16x16x32_bf16 v[64:67], v[180:183], v[212:215], v[64:67]
	v_mfma_f32_16x16x32_bf16 v[80:83], v[180:183], v[204:207], v[80:83]
	v_mfma_f32_16x16x32_bf16 v[84:87], v[172:175], v[204:207], v[84:87]
	v_mfma_f32_16x16x32_bf16 v[100:103], v[172:175], v[196:199], v[100:103]
	v_mfma_f32_16x16x32_bf16 v[96:99], v[180:183], v[196:199], v[96:99]
	v_mfma_f32_16x16x32_bf16 v[112:115], v[180:183], v[188:191], v[112:115]
	v_mfma_f32_16x16x32_bf16 v[116:119], v[172:175], v[188:191], v[116:119]
	s_barrier
	s_add_i32 s22, s53, s28
	v_lshl_add_u64 v[160:161], v[160:161], 0, s[8:9]
	s_mov_b32 m0, s22
	ds_read_b128 v[184:187], v169 offset:49152
	ds_read_b128 v[188:191], v169 offset:50176
	ds_read_b128 v[192:195], v169 offset:51200
	ds_read_b128 v[196:199], v169 offset:52224
	ds_read_b128 v[200:203], v169 offset:53248
	ds_read_b128 v[204:207], v169 offset:54272
	ds_read_b128 v[208:211], v169 offset:55296
	ds_read_b128 v[212:215], v169 offset:56320
	global_load_lds_dwordx4 v[160:161], off
	s_add_i32 m0, s22, 0x2000
	s_add_u32 s20, s20, 0x160080
	v_lshl_add_u64 v[160:161], v[216:217], 0, s[8:9]
	s_addc_u32 s21, s21, 0
	s_add_i32 s22, s54, s28
	global_load_lds_dwordx4 v[160:161], off
	v_lshl_add_u64 v[160:161], s[20:21], 0, v[130:131]
	s_mov_b32 m0, s22
	s_nop 0
	global_load_lds_dwordx4 v[160:161], off
	v_lshl_add_u64 v[160:161], s[20:21], 0, v[134:135]
	s_add_i32 m0, s22, 0x2000
	s_nop 0
	global_load_lds_dwordx4 v[160:161], off
	v_lshl_add_u64 v[160:161], v[218:219], 0, s[8:9]
	s_mov_b32 m0, s39
	s_nop 0
	global_load_lds_dwordx4 v[160:161], off
	v_lshl_add_u64 v[160:161], v[220:221], 0, s[8:9]
	s_mov_b32 m0, s40
	s_nop 0
	global_load_lds_dwordx4 v[160:161], off
	s_waitcnt vmcnt(8)
	s_waitcnt lgkmcnt(0)
	s_barrier
	v_mfma_f32_16x16x32_bf16 v[60:63], v[140:143], v[184:187], v[60:63]
	v_mfma_f32_16x16x32_bf16 v[56:59], v[148:151], v[184:187], v[56:59]
	v_mfma_f32_16x16x32_bf16 v[40:43], v[148:151], v[192:195], v[40:43]
	v_mfma_f32_16x16x32_bf16 v[44:47], v[140:143], v[192:195], v[44:47]
	v_mfma_f32_16x16x32_bf16 v[28:31], v[140:143], v[200:203], v[28:31]
	v_mfma_f32_16x16x32_bf16 v[24:27], v[148:151], v[200:203], v[24:27]
	v_mfma_f32_16x16x32_bf16 v[8:11], v[148:151], v[208:211], v[8:11]
	v_mfma_f32_16x16x32_bf16 v[12:15], v[140:143], v[208:211], v[12:15]
	v_mfma_f32_16x16x32_bf16 v[4:7], v[156:159], v[208:211], v[4:7]
	v_mfma_f32_16x16x32_bf16 v[0:3], v[176:179], v[208:211], v[0:3]
	v_mfma_f32_16x16x32_bf16 v[16:19], v[176:179], v[200:203], v[16:19]
	v_mfma_f32_16x16x32_bf16 v[20:23], v[156:159], v[200:203], v[20:23]
	v_mfma_f32_16x16x32_bf16 v[36:39], v[156:159], v[192:195], v[36:39]
	v_mfma_f32_16x16x32_bf16 v[32:35], v[176:179], v[192:195], v[32:35]
	v_mfma_f32_16x16x32_bf16 v[48:51], v[176:179], v[184:187], v[48:51]
	v_mfma_f32_16x16x32_bf16 v[52:55], v[156:159], v[184:187], v[52:55]
	v_mfma_f32_16x16x32_bf16 v[60:63], v[144:147], v[188:191], v[60:63]
	v_mfma_f32_16x16x32_bf16 v[56:59], v[152:155], v[188:191], v[56:59]
	v_mfma_f32_16x16x32_bf16 v[40:43], v[152:155], v[196:199], v[40:43]
	v_mfma_f32_16x16x32_bf16 v[44:47], v[144:147], v[196:199], v[44:47]
	v_mfma_f32_16x16x32_bf16 v[28:31], v[144:147], v[204:207], v[28:31]
	v_mfma_f32_16x16x32_bf16 v[24:27], v[152:155], v[204:207], v[24:27]
	v_mfma_f32_16x16x32_bf16 v[8:11], v[152:155], v[212:215], v[8:11]
	v_mfma_f32_16x16x32_bf16 v[12:15], v[144:147], v[212:215], v[12:15]
	v_mfma_f32_16x16x32_bf16 v[4:7], v[172:175], v[212:215], v[4:7]
	v_mfma_f32_16x16x32_bf16 v[0:3], v[180:183], v[212:215], v[0:3]
	v_mfma_f32_16x16x32_bf16 v[16:19], v[180:183], v[204:207], v[16:19]
	v_mfma_f32_16x16x32_bf16 v[20:23], v[172:175], v[204:207], v[20:23]
	v_mfma_f32_16x16x32_bf16 v[36:39], v[172:175], v[196:199], v[36:39]
	v_mfma_f32_16x16x32_bf16 v[32:35], v[180:183], v[196:199], v[32:35]
	v_mfma_f32_16x16x32_bf16 v[48:51], v[180:183], v[188:191], v[48:51]
	v_mfma_f32_16x16x32_bf16 v[52:55], v[172:175], v[188:191], v[52:55]
	s_barrier
	s_add_i32 s52, s52, 2
	s_add_u32 s0, s0, 0x100
	s_addc_u32 s1, s1, 0
	s_add_u32 s50, s50, 0x100
	s_addc_u32 s51, s51, 0
	s_cmpk_gt_u32 s52, 0x55
	s_cbranch_scc0 .LBB0_1449
	s_setprio 0
	s_and_b64 vcc, exec, s[10:11]
	s_cbranch_vccz .LBB0_1452
	s_barrier
